# E45: block MFMA order 'hilbert': accumulators visited along a Hilbert curve over the 4(m) x 4(bj,n) grid, k inner; rest as E30
# baseline (speedup 1.0000x reference)
.Lcm1_skip:
.LBB0_225:
	ds_read_b128 v[128:131], v157
	ds_read_b128 v[132:135], v157 offset:1024
	ds_read_b128 v[146:149], v157 offset:2048
	ds_read_b128 v[164:167], v157 offset:3072
	ds_read_b128 v[168:171], v159
	ds_read_b128 v[172:175], v159 offset:1024
	ds_read_b128 v[176:179], v159 offset:2048
	ds_read_b128 v[180:183], v159 offset:3072
	s_add_u32 s36, s22, 0xfff80080
	s_addc_u32 s37, s23, -1
	s_cmp_eq_u32 s78, 28
	s_cselect_b32 s81, s5, s37
	s_cselect_b32 s80, s14, s36
	s_cselect_b32 vcc_hi, s20, s45
	s_cselect_b32 vcc_lo, s21, s24
	s_add_i32 m0, s77, 0xc000
	ds_read_b128 v[184:187], v161
	ds_read_b128 v[188:191], v161 offset:1024
	ds_read_b128 v[192:195], v161 offset:2048
	ds_read_b128 v[196:199], v161 offset:3072
	ds_read_b128 v[200:203], v161 offset:4096
	ds_read_b128 v[204:207], v161 offset:5120
	ds_read_b128 v[208:211], v161 offset:6144
	ds_read_b128 v[212:215], v161 offset:7168
	global_load_lds_dwordx4 v140, s[22:23]
	s_add_i32 m0, s77, 0xe000
	s_nop 0
	s_add_u32 s98, s22, s6
	s_addc_u32 s99, s23, s7
	global_load_lds_dwordx4 v140, s[98:99]
	s_waitcnt vmcnt(8)
	s_waitcnt lgkmcnt(0)
	s_barrier
	s_setprio 1
	s_waitcnt lgkmcnt(0)
	v_mfma_i32_16x16x64_i8 v[0:3], v[128:131], v[184:187], v[0:3]
	v_mfma_i32_16x16x64_i8 v[0:3], v[132:135], v[188:191], v[0:3]
	v_mfma_i32_16x16x64_i8 v[4:7], v[128:131], v[192:195], v[4:7]
	v_mfma_i32_16x16x64_i8 v[4:7], v[132:135], v[196:199], v[4:7]
	v_mfma_i32_16x16x64_i8 v[52:55], v[146:149], v[192:195], v[52:55]
	v_mfma_i32_16x16x64_i8 v[52:55], v[164:167], v[196:199], v[52:55]
	v_mfma_i32_16x16x64_i8 v[56:59], v[146:149], v[184:187], v[56:59]
	v_mfma_i32_16x16x64_i8 v[56:59], v[164:167], v[188:191], v[56:59]
	v_mfma_i32_16x16x64_i8 v[88:91], v[168:171], v[184:187], v[88:91]
	v_mfma_i32_16x16x64_i8 v[88:91], v[172:175], v[188:191], v[88:91]
	v_mfma_i32_16x16x64_i8 v[120:123], v[176:179], v[184:187], v[120:123]
	v_mfma_i32_16x16x64_i8 v[120:123], v[180:183], v[188:191], v[120:123]
	v_mfma_i32_16x16x64_i8 v[116:119], v[176:179], v[192:195], v[116:119]
	v_mfma_i32_16x16x64_i8 v[116:119], v[180:183], v[196:199], v[116:119]
	v_mfma_i32_16x16x64_i8 v[84:87], v[168:171], v[192:195], v[84:87]
	v_mfma_i32_16x16x64_i8 v[84:87], v[172:175], v[196:199], v[84:87]
	s_setprio 0
	s_setprio 1
	v_mfma_i32_16x16x64_i8 v[80:83], v[168:171], v[200:203], v[80:83]
	v_mfma_i32_16x16x64_i8 v[80:83], v[172:175], v[204:207], v[80:83]
	v_mfma_i32_16x16x64_i8 v[112:115], v[176:179], v[200:203], v[112:115]
	v_mfma_i32_16x16x64_i8 v[112:115], v[180:183], v[204:207], v[112:115]
	v_mfma_i32_16x16x64_i8 v[108:111], v[176:179], v[208:211], v[108:111]
	v_mfma_i32_16x16x64_i8 v[108:111], v[180:183], v[212:215], v[108:111]
	v_mfma_i32_16x16x64_i8 v[76:79], v[168:171], v[208:211], v[76:79]
	v_mfma_i32_16x16x64_i8 v[76:79], v[172:175], v[212:215], v[76:79]
	v_mfma_i32_16x16x64_i8 v[44:47], v[146:149], v[208:211], v[44:47]
	v_mfma_i32_16x16x64_i8 v[44:47], v[164:167], v[212:215], v[44:47]
	v_mfma_i32_16x16x64_i8 v[48:51], v[146:149], v[200:203], v[48:51]
	v_mfma_i32_16x16x64_i8 v[48:51], v[164:167], v[204:207], v[48:51]
	s_setprio 2
	s_barrier
	v_mfma_i32_16x16x64_i8 v[12:15], v[128:131], v[200:203], v[12:15]
	v_mfma_i32_16x16x64_i8 v[12:15], v[132:135], v[204:207], v[12:15]
	v_mfma_i32_16x16x64_i8 v[8:11], v[128:131], v[208:211], v[8:11]
	v_mfma_i32_16x16x64_i8 v[8:11], v[132:135], v[212:215], v[8:11]
	s_setprio 0
	s_add_i32 s36, s86, s63
	s_mov_b32 m0, s36
	ds_read_b128 v[184:187], v161 offset:16384
	ds_read_b128 v[188:191], v161 offset:17408
	ds_read_b128 v[192:195], v161 offset:18432
	ds_read_b128 v[196:199], v161 offset:19456
	ds_read_b128 v[200:203], v161 offset:20480
	ds_read_b128 v[204:207], v161 offset:21504
	ds_read_b128 v[208:211], v161 offset:22528
	ds_read_b128 v[212:215], v161 offset:23552
	global_load_lds_dwordx4 v138, vcc
	s_add_i32 m0, s36, 0x2000
	s_add_i32 s36, s87, s63
	s_add_u32 s98, vcc_lo, s6
	s_addc_u32 s99, vcc_hi, s7
	global_load_lds_dwordx4 v138, s[98:99]
	s_mov_b32 m0, s36
	s_nop 0
	s_add_u32 s98, vcc_lo, s8
	s_addc_u32 s99, vcc_hi, s9
	global_load_lds_dwordx4 v138, s[98:99]
	s_add_i32 m0, s36, 0x2000
	s_nop 0
	s_add_u32 s98, vcc_lo, s10
	s_addc_u32 s99, vcc_hi, s11
	global_load_lds_dwordx4 v138, s[98:99]
	s_mov_b32 m0, s77
	s_nop 0
	global_load_lds_dwordx4 v136, s[80:81]
	s_mov_b32 m0, s97
	s_nop 0
	s_add_u32 s98, s80, s6
	s_addc_u32 s99, s81, s7
	global_load_lds_dwordx4 v136, s[98:99]
	s_waitcnt vmcnt(8)
	s_waitcnt lgkmcnt(0)
	s_barrier
	s_setprio 1
	s_waitcnt lgkmcnt(0)
	v_mfma_i32_16x16x64_i8 v[20:23], v[128:131], v[184:187], v[20:23]
	v_mfma_i32_16x16x64_i8 v[20:23], v[132:135], v[188:191], v[20:23]
	v_mfma_i32_16x16x64_i8 v[16:19], v[128:131], v[192:195], v[16:19]
	v_mfma_i32_16x16x64_i8 v[16:19], v[132:135], v[196:199], v[16:19]
	v_mfma_i32_16x16x64_i8 v[36:39], v[146:149], v[192:195], v[36:39]
	v_mfma_i32_16x16x64_i8 v[36:39], v[164:167], v[196:199], v[36:39]
	v_mfma_i32_16x16x64_i8 v[40:43], v[146:149], v[184:187], v[40:43]
	v_mfma_i32_16x16x64_i8 v[40:43], v[164:167], v[188:191], v[40:43]
	v_mfma_i32_16x16x64_i8 v[72:75], v[168:171], v[184:187], v[72:75]
	v_mfma_i32_16x16x64_i8 v[72:75], v[172:175], v[188:191], v[72:75]
	v_mfma_i32_16x16x64_i8 v[104:107], v[176:179], v[184:187], v[104:107]
	v_mfma_i32_16x16x64_i8 v[104:107], v[180:183], v[188:191], v[104:107]
	v_mfma_i32_16x16x64_i8 v[100:103], v[176:179], v[192:195], v[100:103]
	v_mfma_i32_16x16x64_i8 v[100:103], v[180:183], v[196:199], v[100:103]
	v_mfma_i32_16x16x64_i8 v[68:71], v[168:171], v[192:195], v[68:71]
	v_mfma_i32_16x16x64_i8 v[68:71], v[172:175], v[196:199], v[68:71]
	s_setprio 0
	s_setprio 1
	v_mfma_i32_16x16x64_i8 v[64:67], v[168:171], v[200:203], v[64:67]
	v_mfma_i32_16x16x64_i8 v[64:67], v[172:175], v[204:207], v[64:67]
	v_mfma_i32_16x16x64_i8 v[96:99], v[176:179], v[200:203], v[96:99]
	v_mfma_i32_16x16x64_i8 v[96:99], v[180:183], v[204:207], v[96:99]
	v_mfma_i32_16x16x64_i8 v[124:127], v[176:179], v[208:211], v[124:127]
	v_mfma_i32_16x16x64_i8 v[124:127], v[180:183], v[212:215], v[124:127]
	v_mfma_i32_16x16x64_i8 v[92:95], v[168:171], v[208:211], v[92:95]
	v_mfma_i32_16x16x64_i8 v[92:95], v[172:175], v[212:215], v[92:95]
	v_mfma_i32_16x16x64_i8 v[60:63], v[146:149], v[208:211], v[60:63]
	v_mfma_i32_16x16x64_i8 v[60:63], v[164:167], v[212:215], v[60:63]
	v_mfma_i32_16x16x64_i8 v[32:35], v[146:149], v[200:203], v[32:35]
	v_mfma_i32_16x16x64_i8 v[32:35], v[164:167], v[204:207], v[32:35]
	s_setprio 2
	s_barrier
	v_mfma_i32_16x16x64_i8 v[24:27], v[128:131], v[200:203], v[24:27]
	v_mfma_i32_16x16x64_i8 v[24:27], v[132:135], v[204:207], v[24:27]
	v_mfma_i32_16x16x64_i8 v[28:31], v[128:131], v[208:211], v[28:31]
	v_mfma_i32_16x16x64_i8 v[28:31], v[132:135], v[212:215], v[28:31]
	s_setprio 0
	s_add_i32 s36, 0, 0x18000
	v_add_u32_e32 v152, s36, v153
	s_add_i32 s37, 0, 0x1c000
	ds_read_b128 v[128:131], v152
	ds_read_b128 v[132:135], v152 offset:1024
	ds_read_b128 v[146:149], v152 offset:2048
	ds_read_b128 v[164:167], v152 offset:3072
	v_add_u32_e32 v152, s37, v153
	ds_read_b128 v[168:171], v152
	ds_read_b128 v[172:175], v152 offset:1024
	ds_read_b128 v[176:179], v152 offset:2048
	ds_read_b128 v[180:183], v152 offset:3072
	s_mov_b32 m0, s33
	ds_read_b128 v[184:187], v161 offset:32768
	ds_read_b128 v[188:191], v161 offset:33792
	ds_read_b128 v[192:195], v161 offset:34816
	ds_read_b128 v[196:199], v161 offset:35840
	ds_read_b128 v[200:203], v161 offset:36864
	ds_read_b128 v[204:207], v161 offset:37888
	ds_read_b128 v[208:211], v161 offset:38912
	ds_read_b128 v[212:215], v161 offset:39936
	s_add_u32 s98, s80, s8
	s_addc_u32 s99, s81, s9
	global_load_lds_dwordx4 v136, s[98:99]
	s_mov_b32 m0, s93
	s_nop 0
	s_add_u32 s98, s80, s10
	s_addc_u32 s99, s81, s11
	global_load_lds_dwordx4 v136, s[98:99]
	s_waitcnt vmcnt(8)
	s_waitcnt lgkmcnt(0)
	s_barrier
	s_setprio 1
	s_waitcnt lgkmcnt(0)
	v_mfma_i32_16x16x64_i8 v[0:3], v[128:131], v[184:187], v[0:3]
	v_mfma_i32_16x16x64_i8 v[0:3], v[132:135], v[188:191], v[0:3]
	v_mfma_i32_16x16x64_i8 v[4:7], v[128:131], v[192:195], v[4:7]
	v_mfma_i32_16x16x64_i8 v[4:7], v[132:135], v[196:199], v[4:7]
	v_mfma_i32_16x16x64_i8 v[52:55], v[146:149], v[192:195], v[52:55]
	v_mfma_i32_16x16x64_i8 v[52:55], v[164:167], v[196:199], v[52:55]
	v_mfma_i32_16x16x64_i8 v[56:59], v[146:149], v[184:187], v[56:59]
	v_mfma_i32_16x16x64_i8 v[56:59], v[164:167], v[188:191], v[56:59]
	v_mfma_i32_16x16x64_i8 v[88:91], v[168:171], v[184:187], v[88:91]
	v_mfma_i32_16x16x64_i8 v[88:91], v[172:175], v[188:191], v[88:91]
	v_mfma_i32_16x16x64_i8 v[120:123], v[176:179], v[184:187], v[120:123]
	v_mfma_i32_16x16x64_i8 v[120:123], v[180:183], v[188:191], v[120:123]
	v_mfma_i32_16x16x64_i8 v[116:119], v[176:179], v[192:195], v[116:119]
	v_mfma_i32_16x16x64_i8 v[116:119], v[180:183], v[196:199], v[116:119]
	v_mfma_i32_16x16x64_i8 v[84:87], v[168:171], v[192:195], v[84:87]
	v_mfma_i32_16x16x64_i8 v[84:87], v[172:175], v[196:199], v[84:87]
	s_setprio 0
	s_setprio 1
	v_mfma_i32_16x16x64_i8 v[80:83], v[168:171], v[200:203], v[80:83]
	v_mfma_i32_16x16x64_i8 v[80:83], v[172:175], v[204:207], v[80:83]
	v_mfma_i32_16x16x64_i8 v[112:115], v[176:179], v[200:203], v[112:115]
	v_mfma_i32_16x16x64_i8 v[112:115], v[180:183], v[204:207], v[112:115]
	v_mfma_i32_16x16x64_i8 v[108:111], v[176:179], v[208:211], v[108:111]
	v_mfma_i32_16x16x64_i8 v[108:111], v[180:183], v[212:215], v[108:111]
	v_mfma_i32_16x16x64_i8 v[76:79], v[168:171], v[208:211], v[76:79]
	v_mfma_i32_16x16x64_i8 v[76:79], v[172:175], v[212:215], v[76:79]
	v_mfma_i32_16x16x64_i8 v[44:47], v[146:149], v[208:211], v[44:47]
	v_mfma_i32_16x16x64_i8 v[44:47], v[164:167], v[212:215], v[44:47]
	v_mfma_i32_16x16x64_i8 v[48:51], v[146:149], v[200:203], v[48:51]
	v_mfma_i32_16x16x64_i8 v[48:51], v[164:167], v[204:207], v[48:51]
	s_setprio 2
	s_barrier
	v_mfma_i32_16x16x64_i8 v[12:15], v[128:131], v[200:203], v[12:15]
	v_mfma_i32_16x16x64_i8 v[12:15], v[132:135], v[204:207], v[12:15]
	v_mfma_i32_16x16x64_i8 v[8:11], v[128:131], v[208:211], v[8:11]
	v_mfma_i32_16x16x64_i8 v[8:11], v[132:135], v[212:215], v[8:11]
	s_setprio 0
	s_add_i32 s36, s36, s63
	s_mov_b32 m0, s36
	ds_read_b128 v[184:187], v161 offset:49152
	ds_read_b128 v[188:191], v161 offset:50176
	ds_read_b128 v[192:195], v161 offset:51200
	ds_read_b128 v[196:199], v161 offset:52224
	ds_read_b128 v[200:203], v161 offset:53248
	ds_read_b128 v[204:207], v161 offset:54272
	ds_read_b128 v[208:211], v161 offset:55296
	ds_read_b128 v[212:215], v161 offset:56320
	s_add_u32 s98, vcc_lo, s46
	s_addc_u32 s99, vcc_hi, s47
	global_load_lds_dwordx4 v138, s[98:99]
	s_add_i32 m0, s36, 0x2000
	s_add_i32 s36, s37, s63
	s_add_u32 s98, vcc_lo, s48
	s_addc_u32 s99, vcc_hi, s49
	global_load_lds_dwordx4 v138, s[98:99]
	s_mov_b32 m0, s36
	s_add_u32 s98, vcc_lo, s54
	s_addc_u32 s99, vcc_hi, s55
	global_load_lds_dwordx4 v138, s[98:99]
	s_add_i32 m0, s36, 0x2000
	s_nop 0
	s_add_u32 s98, vcc_lo, s56
	s_addc_u32 s99, vcc_hi, s57
	global_load_lds_dwordx4 v138, s[98:99]
	s_mov_b32 m0, s95
	s_nop 0
	s_add_u32 s98, s80, s46
	s_addc_u32 s99, s81, s47
	global_load_lds_dwordx4 v136, s[98:99]
	s_mov_b32 m0, s82
	s_nop 0
	s_add_u32 s98, s80, s48
	s_addc_u32 s99, s81, s49
	global_load_lds_dwordx4 v136, s[98:99]
	s_waitcnt vmcnt(8)
	s_waitcnt lgkmcnt(0)
	s_barrier
	s_setprio 1
	s_waitcnt lgkmcnt(0)
	v_mfma_i32_16x16x64_i8 v[20:23], v[128:131], v[184:187], v[20:23]
	v_mfma_i32_16x16x64_i8 v[20:23], v[132:135], v[188:191], v[20:23]
	v_mfma_i32_16x16x64_i8 v[16:19], v[128:131], v[192:195], v[16:19]
	v_mfma_i32_16x16x64_i8 v[16:19], v[132:135], v[196:199], v[16:19]
	v_mfma_i32_16x16x64_i8 v[36:39], v[146:149], v[192:195], v[36:39]
	v_mfma_i32_16x16x64_i8 v[36:39], v[164:167], v[196:199], v[36:39]
	v_mfma_i32_16x16x64_i8 v[40:43], v[146:149], v[184:187], v[40:43]
	v_mfma_i32_16x16x64_i8 v[40:43], v[164:167], v[188:191], v[40:43]
	v_mfma_i32_16x16x64_i8 v[72:75], v[168:171], v[184:187], v[72:75]
	v_mfma_i32_16x16x64_i8 v[72:75], v[172:175], v[188:191], v[72:75]
	v_mfma_i32_16x16x64_i8 v[104:107], v[176:179], v[184:187], v[104:107]
	v_mfma_i32_16x16x64_i8 v[104:107], v[180:183], v[188:191], v[104:107]
	v_mfma_i32_16x16x64_i8 v[100:103], v[176:179], v[192:195], v[100:103]
	v_mfma_i32_16x16x64_i8 v[100:103], v[180:183], v[196:199], v[100:103]
	v_mfma_i32_16x16x64_i8 v[68:71], v[168:171], v[192:195], v[68:71]
	v_mfma_i32_16x16x64_i8 v[68:71], v[172:175], v[196:199], v[68:71]
	s_setprio 0
	s_setprio 1
	v_mfma_i32_16x16x64_i8 v[64:67], v[168:171], v[200:203], v[64:67]
	v_mfma_i32_16x16x64_i8 v[64:67], v[172:175], v[204:207], v[64:67]
	v_mfma_i32_16x16x64_i8 v[96:99], v[176:179], v[200:203], v[96:99]
	v_mfma_i32_16x16x64_i8 v[96:99], v[180:183], v[204:207], v[96:99]
	v_mfma_i32_16x16x64_i8 v[124:127], v[176:179], v[208:211], v[124:127]
	v_mfma_i32_16x16x64_i8 v[124:127], v[180:183], v[212:215], v[124:127]
	v_mfma_i32_16x16x64_i8 v[92:95], v[168:171], v[208:211], v[92:95]
	v_mfma_i32_16x16x64_i8 v[92:95], v[172:175], v[212:215], v[92:95]
	v_mfma_i32_16x16x64_i8 v[60:63], v[146:149], v[208:211], v[60:63]
	v_mfma_i32_16x16x64_i8 v[60:63], v[164:167], v[212:215], v[60:63]
	v_mfma_i32_16x16x64_i8 v[32:35], v[146:149], v[200:203], v[32:35]
	v_mfma_i32_16x16x64_i8 v[32:35], v[164:167], v[204:207], v[32:35]
	s_setprio 2
	s_barrier
	v_mfma_i32_16x16x64_i8 v[24:27], v[128:131], v[200:203], v[24:27]
	v_mfma_i32_16x16x64_i8 v[24:27], v[132:135], v[204:207], v[24:27]
	v_mfma_i32_16x16x64_i8 v[28:31], v[128:131], v[208:211], v[28:31]
	v_mfma_i32_16x16x64_i8 v[28:31], v[132:135], v[212:215], v[28:31]
	s_setprio 0
	s_add_i32 s78, s78, 2
	s_add_u32 s24, s24, 0x100
	s_addc_u32 s45, s45, 0
	s_add_u32 s22, s22, 0x100
	s_addc_u32 s23, s23, 0
	s_cmp_gt_u32 s78, 29
	s_cbranch_scc0 .LBB0_225
	v_readlane_b32 s14, v250, 9
	v_readlane_b32 s15, v250, 10
	s_and_b64 vcc, exec, s[14:15]
	s_cbranch_vccz .LBB0_228
	s_barrier

.LBB0_298:
	ds_read_b128 v[128:131], v153
	ds_read_b128 v[132:135], v153 offset:1024
	ds_read_b128 v[146:149], v153 offset:2048
	ds_read_b128 v[158:161], v153 offset:3072
	ds_read_b128 v[162:165], v154
	ds_read_b128 v[166:169], v154 offset:1024
	ds_read_b128 v[170:173], v154 offset:2048
	ds_read_b128 v[174:177], v154 offset:3072
	s_add_u32 s36, s78, 0xfff00080
	s_addc_u32 s37, s79, -1
	s_cmp_eq_u32 s81, 60
	s_cselect_b32 s97, s5, s37
	s_cselect_b32 s96, s14, s36
	s_cselect_b32 vcc_hi, s20, s80
	s_cselect_b32 vcc_lo, s21, s22
	s_add_i32 m0, s33, 0xc000
	ds_read_b128 v[178:181], v155
	ds_read_b128 v[182:185], v155 offset:1024
	ds_read_b128 v[186:189], v155 offset:2048
	ds_read_b128 v[190:193], v155 offset:3072
	ds_read_b128 v[194:197], v155 offset:4096
	ds_read_b128 v[198:201], v155 offset:5120
	ds_read_b128 v[202:205], v155 offset:6144
	ds_read_b128 v[206:209], v155 offset:7168
	global_load_lds_dwordx4 v140, s[78:79]
	s_add_i32 m0, s33, 0xe000
	s_nop 0
	s_add_u32 s98, s78, s0
	s_addc_u32 s99, s79, s1
	global_load_lds_dwordx4 v140, s[98:99]
	s_waitcnt vmcnt(8)
	s_waitcnt lgkmcnt(0)
	s_barrier
	s_setprio 1
	s_waitcnt lgkmcnt(0)
	v_mfma_f32_16x16x32_bf16 v[124:127], v[128:131], v[178:181], v[124:127]
	v_mfma_f32_16x16x32_bf16 v[124:127], v[132:135], v[182:185], v[124:127]
	v_mfma_f32_16x16x32_bf16 v[112:115], v[128:131], v[186:189], v[112:115]
	v_mfma_f32_16x16x32_bf16 v[112:115], v[132:135], v[190:193], v[112:115]
	v_mfma_f32_16x16x32_bf16 v[108:111], v[146:149], v[186:189], v[108:111]
	v_mfma_f32_16x16x32_bf16 v[108:111], v[158:161], v[190:193], v[108:111]
	v_mfma_f32_16x16x32_bf16 v[120:123], v[146:149], v[178:181], v[120:123]
	v_mfma_f32_16x16x32_bf16 v[120:123], v[158:161], v[182:185], v[120:123]
	v_mfma_f32_16x16x32_bf16 v[116:119], v[162:165], v[178:181], v[116:119]
	v_mfma_f32_16x16x32_bf16 v[116:119], v[166:169], v[182:185], v[116:119]
	v_mfma_f32_16x16x32_bf16 v[104:107], v[170:173], v[178:181], v[104:107]
	v_mfma_f32_16x16x32_bf16 v[104:107], v[174:177], v[182:185], v[104:107]
	v_mfma_f32_16x16x32_bf16 v[88:91], v[170:173], v[186:189], v[88:91]
	v_mfma_f32_16x16x32_bf16 v[88:91], v[174:177], v[190:193], v[88:91]
	v_mfma_f32_16x16x32_bf16 v[96:99], v[162:165], v[186:189], v[96:99]
	v_mfma_f32_16x16x32_bf16 v[96:99], v[166:169], v[190:193], v[96:99]
	s_setprio 0
	s_setprio 1
	v_mfma_f32_16x16x32_bf16 v[80:83], v[162:165], v[194:197], v[80:83]
	v_mfma_f32_16x16x32_bf16 v[80:83], v[166:169], v[198:201], v[80:83]
	v_mfma_f32_16x16x32_bf16 v[72:75], v[170:173], v[194:197], v[72:75]
	v_mfma_f32_16x16x32_bf16 v[72:75], v[174:177], v[198:201], v[72:75]
	v_mfma_f32_16x16x32_bf16 v[64:67], v[170:173], v[202:205], v[64:67]
	v_mfma_f32_16x16x32_bf16 v[64:67], v[174:177], v[206:209], v[64:67]
	v_mfma_f32_16x16x32_bf16 v[68:71], v[162:165], v[202:205], v[68:71]
	v_mfma_f32_16x16x32_bf16 v[68:71], v[166:169], v[206:209], v[68:71]
	v_mfma_f32_16x16x32_bf16 v[76:79], v[146:149], v[202:205], v[76:79]
	v_mfma_f32_16x16x32_bf16 v[76:79], v[158:161], v[206:209], v[76:79]
	v_mfma_f32_16x16x32_bf16 v[92:95], v[146:149], v[194:197], v[92:95]
	v_mfma_f32_16x16x32_bf16 v[92:95], v[158:161], v[198:201], v[92:95]
	s_setprio 2
	s_barrier
	v_mfma_f32_16x16x32_bf16 v[100:103], v[128:131], v[194:197], v[100:103]
	v_mfma_f32_16x16x32_bf16 v[100:103], v[132:135], v[198:201], v[100:103]
	v_mfma_f32_16x16x32_bf16 v[84:87], v[128:131], v[202:205], v[84:87]
	v_mfma_f32_16x16x32_bf16 v[84:87], v[132:135], v[206:209], v[84:87]
	s_setprio 0
	s_add_i32 s36, s82, s63
	s_mov_b32 m0, s36
	ds_read_b128 v[178:181], v155 offset:16384
	ds_read_b128 v[182:185], v155 offset:17408
	ds_read_b128 v[186:189], v155 offset:18432
	ds_read_b128 v[190:193], v155 offset:19456
	ds_read_b128 v[194:197], v155 offset:20480
	ds_read_b128 v[198:201], v155 offset:21504
	ds_read_b128 v[202:205], v155 offset:22528
	ds_read_b128 v[206:209], v155 offset:23552
	global_load_lds_dwordx4 v138, vcc
	s_add_i32 m0, s36, 0x2000
	s_add_i32 s36, s83, s63
	s_add_u32 s98, vcc_lo, s0
	s_addc_u32 s99, vcc_hi, s1
	global_load_lds_dwordx4 v138, s[98:99]
	s_mov_b32 m0, s36
	s_nop 0
	s_add_u32 s98, vcc_lo, s6
	s_addc_u32 s99, vcc_hi, s7
	global_load_lds_dwordx4 v138, s[98:99]
	s_add_i32 m0, s36, 0x2000
	s_nop 0
	s_add_u32 s98, vcc_lo, s8
	s_addc_u32 s99, vcc_hi, s9
	global_load_lds_dwordx4 v138, s[98:99]
	s_mov_b32 m0, s33
	s_nop 0
	global_load_lds_dwordx4 v136, s[96:97]
	s_mov_b32 m0, s55
	s_nop 0
	s_add_u32 s98, s96, s0
	s_addc_u32 s99, s97, s1
	global_load_lds_dwordx4 v136, s[98:99]
	s_waitcnt vmcnt(8)
	s_waitcnt lgkmcnt(0)
	s_barrier
	s_setprio 1
	s_waitcnt lgkmcnt(0)
	v_mfma_f32_16x16x32_bf16 v[60:63], v[128:131], v[178:181], v[60:63]
	v_mfma_f32_16x16x32_bf16 v[60:63], v[132:135], v[182:185], v[60:63]
	v_mfma_f32_16x16x32_bf16 v[52:55], v[128:131], v[186:189], v[52:55]
	v_mfma_f32_16x16x32_bf16 v[52:55], v[132:135], v[190:193], v[52:55]
	v_mfma_f32_16x16x32_bf16 v[44:47], v[146:149], v[186:189], v[44:47]
	v_mfma_f32_16x16x32_bf16 v[44:47], v[158:161], v[190:193], v[44:47]
	v_mfma_f32_16x16x32_bf16 v[56:59], v[146:149], v[178:181], v[56:59]
	v_mfma_f32_16x16x32_bf16 v[56:59], v[158:161], v[182:185], v[56:59]
	v_mfma_f32_16x16x32_bf16 v[48:51], v[162:165], v[178:181], v[48:51]
	v_mfma_f32_16x16x32_bf16 v[48:51], v[166:169], v[182:185], v[48:51]
	v_mfma_f32_16x16x32_bf16 v[40:43], v[170:173], v[178:181], v[40:43]
	v_mfma_f32_16x16x32_bf16 v[40:43], v[174:177], v[182:185], v[40:43]
	v_mfma_f32_16x16x32_bf16 v[24:27], v[170:173], v[186:189], v[24:27]
	v_mfma_f32_16x16x32_bf16 v[24:27], v[174:177], v[190:193], v[24:27]
	v_mfma_f32_16x16x32_bf16 v[32:35], v[162:165], v[186:189], v[32:35]
	v_mfma_f32_16x16x32_bf16 v[32:35], v[166:169], v[190:193], v[32:35]
	s_setprio 0
	s_setprio 1
	v_mfma_f32_16x16x32_bf16 v[16:19], v[162:165], v[194:197], v[16:19]
	v_mfma_f32_16x16x32_bf16 v[16:19], v[166:169], v[198:201], v[16:19]
	v_mfma_f32_16x16x32_bf16 v[8:11], v[170:173], v[194:197], v[8:11]
	v_mfma_f32_16x16x32_bf16 v[8:11], v[174:177], v[198:201], v[8:11]
	v_mfma_f32_16x16x32_bf16 v[0:3], v[170:173], v[202:205], v[0:3]
	v_mfma_f32_16x16x32_bf16 v[0:3], v[174:177], v[206:209], v[0:3]
	v_mfma_f32_16x16x32_bf16 v[4:7], v[162:165], v[202:205], v[4:7]
	v_mfma_f32_16x16x32_bf16 v[4:7], v[166:169], v[206:209], v[4:7]
	v_mfma_f32_16x16x32_bf16 v[12:15], v[146:149], v[202:205], v[12:15]
	v_mfma_f32_16x16x32_bf16 v[12:15], v[158:161], v[206:209], v[12:15]
	v_mfma_f32_16x16x32_bf16 v[28:31], v[146:149], v[194:197], v[28:31]
	v_mfma_f32_16x16x32_bf16 v[28:31], v[158:161], v[198:201], v[28:31]
	s_setprio 2
	s_barrier
	v_mfma_f32_16x16x32_bf16 v[36:39], v[128:131], v[194:197], v[36:39]
	v_mfma_f32_16x16x32_bf16 v[36:39], v[132:135], v[198:201], v[36:39]
	v_mfma_f32_16x16x32_bf16 v[20:23], v[128:131], v[202:205], v[20:23]
	v_mfma_f32_16x16x32_bf16 v[20:23], v[132:135], v[206:209], v[20:23]
	s_setprio 0
	s_add_i32 s36, 0, 0x18000
	v_add_u32_e32 v157, s36, v152
	s_add_i32 s37, 0, 0x1c000
	ds_read_b128 v[128:131], v157
	ds_read_b128 v[132:135], v157 offset:1024
	ds_read_b128 v[146:149], v157 offset:2048
	ds_read_b128 v[158:161], v157 offset:3072
	v_add_u32_e32 v157, s37, v152
	ds_read_b128 v[162:165], v157
	ds_read_b128 v[166:169], v157 offset:1024
	ds_read_b128 v[170:173], v157 offset:2048
	ds_read_b128 v[174:177], v157 offset:3072
	s_mov_b32 m0, s57
	ds_read_b128 v[178:181], v155 offset:32768
	ds_read_b128 v[182:185], v155 offset:33792
	ds_read_b128 v[186:189], v155 offset:34816
	ds_read_b128 v[190:193], v155 offset:35840
	ds_read_b128 v[194:197], v155 offset:36864
	ds_read_b128 v[198:201], v155 offset:37888
	ds_read_b128 v[202:205], v155 offset:38912
	ds_read_b128 v[206:209], v155 offset:39936
	s_add_u32 s98, s96, s6
	s_addc_u32 s99, s97, s7
	global_load_lds_dwordx4 v136, s[98:99]
	s_mov_b32 m0, s59
	s_nop 0
	s_add_u32 s98, s96, s8
	s_addc_u32 s99, s97, s9
	global_load_lds_dwordx4 v136, s[98:99]
	s_waitcnt vmcnt(8)
	s_waitcnt lgkmcnt(0)
	s_barrier
	s_setprio 1
	s_waitcnt lgkmcnt(0)
	v_mfma_f32_16x16x32_bf16 v[124:127], v[128:131], v[178:181], v[124:127]
	v_mfma_f32_16x16x32_bf16 v[124:127], v[132:135], v[182:185], v[124:127]
	v_mfma_f32_16x16x32_bf16 v[112:115], v[128:131], v[186:189], v[112:115]
	v_mfma_f32_16x16x32_bf16 v[112:115], v[132:135], v[190:193], v[112:115]
	v_mfma_f32_16x16x32_bf16 v[108:111], v[146:149], v[186:189], v[108:111]
	v_mfma_f32_16x16x32_bf16 v[108:111], v[158:161], v[190:193], v[108:111]
	v_mfma_f32_16x16x32_bf16 v[120:123], v[146:149], v[178:181], v[120:123]
	v_mfma_f32_16x16x32_bf16 v[120:123], v[158:161], v[182:185], v[120:123]
	v_mfma_f32_16x16x32_bf16 v[116:119], v[162:165], v[178:181], v[116:119]
	v_mfma_f32_16x16x32_bf16 v[116:119], v[166:169], v[182:185], v[116:119]
	v_mfma_f32_16x16x32_bf16 v[104:107], v[170:173], v[178:181], v[104:107]
	v_mfma_f32_16x16x32_bf16 v[104:107], v[174:177], v[182:185], v[104:107]
	v_mfma_f32_16x16x32_bf16 v[88:91], v[170:173], v[186:189], v[88:91]
	v_mfma_f32_16x16x32_bf16 v[88:91], v[174:177], v[190:193], v[88:91]
	v_mfma_f32_16x16x32_bf16 v[96:99], v[162:165], v[186:189], v[96:99]
	v_mfma_f32_16x16x32_bf16 v[96:99], v[166:169], v[190:193], v[96:99]
	s_setprio 0
	s_setprio 1
	v_mfma_f32_16x16x32_bf16 v[80:83], v[162:165], v[194:197], v[80:83]
	v_mfma_f32_16x16x32_bf16 v[80:83], v[166:169], v[198:201], v[80:83]
	v_mfma_f32_16x16x32_bf16 v[72:75], v[170:173], v[194:197], v[72:75]
	v_mfma_f32_16x16x32_bf16 v[72:75], v[174:177], v[198:201], v[72:75]
	v_mfma_f32_16x16x32_bf16 v[64:67], v[170:173], v[202:205], v[64:67]
	v_mfma_f32_16x16x32_bf16 v[64:67], v[174:177], v[206:209], v[64:67]
	v_mfma_f32_16x16x32_bf16 v[68:71], v[162:165], v[202:205], v[68:71]
	v_mfma_f32_16x16x32_bf16 v[68:71], v[166:169], v[206:209], v[68:71]
	v_mfma_f32_16x16x32_bf16 v[76:79], v[146:149], v[202:205], v[76:79]
	v_mfma_f32_16x16x32_bf16 v[76:79], v[158:161], v[206:209], v[76:79]
	v_mfma_f32_16x16x32_bf16 v[92:95], v[146:149], v[194:197], v[92:95]
	v_mfma_f32_16x16x32_bf16 v[92:95], v[158:161], v[198:201], v[92:95]
	s_setprio 2
	s_barrier
	v_mfma_f32_16x16x32_bf16 v[100:103], v[128:131], v[194:197], v[100:103]
	v_mfma_f32_16x16x32_bf16 v[100:103], v[132:135], v[198:201], v[100:103]
	v_mfma_f32_16x16x32_bf16 v[84:87], v[128:131], v[202:205], v[84:87]
	v_mfma_f32_16x16x32_bf16 v[84:87], v[132:135], v[206:209], v[84:87]
	s_setprio 0
	s_add_i32 s36, s36, s63
	s_mov_b32 m0, s36
	ds_read_b128 v[178:181], v155 offset:49152
	ds_read_b128 v[182:185], v155 offset:50176
	ds_read_b128 v[186:189], v155 offset:51200
	ds_read_b128 v[190:193], v155 offset:52224
	ds_read_b128 v[194:197], v155 offset:53248
	ds_read_b128 v[198:201], v155 offset:54272
	ds_read_b128 v[202:205], v155 offset:55296
	ds_read_b128 v[206:209], v155 offset:56320
	s_add_u32 s98, vcc_lo, s24
	s_addc_u32 s99, vcc_hi, s25
	global_load_lds_dwordx4 v138, s[98:99]
	s_add_i32 m0, s36, 0x2000
	s_add_i32 s36, s37, s63
	s_add_u32 s98, vcc_lo, s34
	s_addc_u32 s99, vcc_hi, s35
	global_load_lds_dwordx4 v138, s[98:99]
	s_mov_b32 m0, s36
	s_add_u32 s98, vcc_lo, s12
	s_addc_u32 s99, vcc_hi, s13
	global_load_lds_dwordx4 v138, s[98:99]
	s_add_i32 m0, s36, 0x2000
	s_nop 0
	s_add_u32 s98, vcc_lo, s18
	s_addc_u32 s99, vcc_hi, s19
	global_load_lds_dwordx4 v138, s[98:99]
	s_mov_b32 m0, s68
	s_nop 0
	s_add_u32 s98, s96, s24
	s_addc_u32 s99, s97, s25
	global_load_lds_dwordx4 v136, s[98:99]
	s_mov_b32 m0, s69
	s_nop 0
	s_add_u32 s98, s96, s34
	s_addc_u32 s99, s97, s35
	global_load_lds_dwordx4 v136, s[98:99]
	s_waitcnt vmcnt(8)
	s_waitcnt lgkmcnt(0)
	s_barrier
	s_setprio 1
	s_waitcnt lgkmcnt(0)
	v_mfma_f32_16x16x32_bf16 v[60:63], v[128:131], v[178:181], v[60:63]
	v_mfma_f32_16x16x32_bf16 v[60:63], v[132:135], v[182:185], v[60:63]
	v_mfma_f32_16x16x32_bf16 v[52:55], v[128:131], v[186:189], v[52:55]
	v_mfma_f32_16x16x32_bf16 v[52:55], v[132:135], v[190:193], v[52:55]
	v_mfma_f32_16x16x32_bf16 v[44:47], v[146:149], v[186:189], v[44:47]
	v_mfma_f32_16x16x32_bf16 v[44:47], v[158:161], v[190:193], v[44:47]
	v_mfma_f32_16x16x32_bf16 v[56:59], v[146:149], v[178:181], v[56:59]
	v_mfma_f32_16x16x32_bf16 v[56:59], v[158:161], v[182:185], v[56:59]
	v_mfma_f32_16x16x32_bf16 v[48:51], v[162:165], v[178:181], v[48:51]
	v_mfma_f32_16x16x32_bf16 v[48:51], v[166:169], v[182:185], v[48:51]
	v_mfma_f32_16x16x32_bf16 v[40:43], v[170:173], v[178:181], v[40:43]
	v_mfma_f32_16x16x32_bf16 v[40:43], v[174:177], v[182:185], v[40:43]
	v_mfma_f32_16x16x32_bf16 v[24:27], v[170:173], v[186:189], v[24:27]
	v_mfma_f32_16x16x32_bf16 v[24:27], v[174:177], v[190:193], v[24:27]
	v_mfma_f32_16x16x32_bf16 v[32:35], v[162:165], v[186:189], v[32:35]
	v_mfma_f32_16x16x32_bf16 v[32:35], v[166:169], v[190:193], v[32:35]
	s_setprio 0
	s_setprio 1
	v_mfma_f32_16x16x32_bf16 v[16:19], v[162:165], v[194:197], v[16:19]
	v_mfma_f32_16x16x32_bf16 v[16:19], v[166:169], v[198:201], v[16:19]
	v_mfma_f32_16x16x32_bf16 v[8:11], v[170:173], v[194:197], v[8:11]
	v_mfma_f32_16x16x32_bf16 v[8:11], v[174:177], v[198:201], v[8:11]
	v_mfma_f32_16x16x32_bf16 v[0:3], v[170:173], v[202:205], v[0:3]
	v_mfma_f32_16x16x32_bf16 v[0:3], v[174:177], v[206:209], v[0:3]
	v_mfma_f32_16x16x32_bf16 v[4:7], v[162:165], v[202:205], v[4:7]
	v_mfma_f32_16x16x32_bf16 v[4:7], v[166:169], v[206:209], v[4:7]
	v_mfma_f32_16x16x32_bf16 v[12:15], v[146:149], v[202:205], v[12:15]
	v_mfma_f32_16x16x32_bf16 v[12:15], v[158:161], v[206:209], v[12:15]
	v_mfma_f32_16x16x32_bf16 v[28:31], v[146:149], v[194:197], v[28:31]
	v_mfma_f32_16x16x32_bf16 v[28:31], v[158:161], v[198:201], v[28:31]
	s_setprio 2
	s_barrier
	v_mfma_f32_16x16x32_bf16 v[36:39], v[128:131], v[194:197], v[36:39]
	v_mfma_f32_16x16x32_bf16 v[36:39], v[132:135], v[198:201], v[36:39]
	v_mfma_f32_16x16x32_bf16 v[20:23], v[128:131], v[202:205], v[20:23]
	v_mfma_f32_16x16x32_bf16 v[20:23], v[132:135], v[206:209], v[20:23]
	s_setprio 0
	s_add_i32 s81, s81, 2
	s_add_u32 s22, s22, 0x100
	s_addc_u32 s80, s80, 0
	s_add_u32 s78, s78, 0x100
	s_addc_u32 s79, s79, 0
	s_cmp_gt_u32 s81, 61
	s_cbranch_scc0 .LBB0_298
	s_and_b64 vcc, exec, s[26:27]
	s_cbranch_vccz .LBB0_301
	s_barrier

.LBB0_627:
	ds_read_b128 v[128:131], v151
	ds_read_b128 v[142:145], v151 offset:1024
	ds_read_b128 v[146:149], v151 offset:2048
	ds_read_b128 v[154:157], v151 offset:3072
	ds_read_b128 v[158:161], v152
	ds_read_b128 v[162:165], v152 offset:1024
	ds_read_b128 v[166:169], v152 offset:2048
	ds_read_b128 v[170:173], v152 offset:3072
	s_add_u32 s50, s60, 0xfff00080
	s_addc_u32 s51, s61, -1
	s_cmp_eq_u32 s62, 60
	s_cselect_b32 s77, s5, s51
	s_cselect_b32 s76, s49, s50
	s_cselect_b32 s79, s47, s75
	s_cselect_b32 s78, s59, s74
	s_add_i32 m0, s20, 0xc000
	ds_read_b128 v[174:177], v153
	ds_read_b128 v[178:181], v153 offset:1024
	ds_read_b128 v[182:185], v153 offset:2048
	ds_read_b128 v[186:189], v153 offset:3072
	ds_read_b128 v[190:193], v153 offset:4096
	ds_read_b128 v[194:197], v153 offset:5120
	ds_read_b128 v[198:201], v153 offset:6144
	ds_read_b128 v[202:205], v153 offset:7168
	global_load_lds_dwordx4 v136, s[60:61]
	s_add_i32 m0, s20, 0xe000
	s_nop 0
	s_add_u32 s98, s60, s6
	s_addc_u32 s99, s61, s7
	global_load_lds_dwordx4 v136, s[98:99]
	s_waitcnt vmcnt(8)
	s_waitcnt lgkmcnt(0)
	s_barrier
	s_setprio 1
	s_waitcnt lgkmcnt(0)
	v_mfma_f32_16x16x32_bf16 v[124:127], v[128:131], v[174:177], v[124:127]
	v_mfma_f32_16x16x32_bf16 v[124:127], v[142:145], v[178:181], v[124:127]
	v_mfma_f32_16x16x32_bf16 v[116:119], v[128:131], v[182:185], v[116:119]
	v_mfma_f32_16x16x32_bf16 v[116:119], v[142:145], v[186:189], v[116:119]
	v_mfma_f32_16x16x32_bf16 v[112:115], v[146:149], v[182:185], v[112:115]
	v_mfma_f32_16x16x32_bf16 v[112:115], v[154:157], v[186:189], v[112:115]
	v_mfma_f32_16x16x32_bf16 v[120:123], v[146:149], v[174:177], v[120:123]
	v_mfma_f32_16x16x32_bf16 v[120:123], v[154:157], v[178:181], v[120:123]
	v_mfma_f32_16x16x32_bf16 v[92:95], v[158:161], v[174:177], v[92:95]
	v_mfma_f32_16x16x32_bf16 v[92:95], v[162:165], v[178:181], v[92:95]
	v_mfma_f32_16x16x32_bf16 v[88:91], v[166:169], v[174:177], v[88:91]
	v_mfma_f32_16x16x32_bf16 v[88:91], v[170:173], v[178:181], v[88:91]
	v_mfma_f32_16x16x32_bf16 v[80:83], v[166:169], v[182:185], v[80:83]
	v_mfma_f32_16x16x32_bf16 v[80:83], v[170:173], v[186:189], v[80:83]
	v_mfma_f32_16x16x32_bf16 v[84:87], v[158:161], v[182:185], v[84:87]
	v_mfma_f32_16x16x32_bf16 v[84:87], v[162:165], v[186:189], v[84:87]
	s_setprio 0
	s_setprio 1
	v_mfma_f32_16x16x32_bf16 v[76:79], v[158:161], v[190:193], v[76:79]
	v_mfma_f32_16x16x32_bf16 v[76:79], v[162:165], v[194:197], v[76:79]
	v_mfma_f32_16x16x32_bf16 v[72:75], v[166:169], v[190:193], v[72:75]
	v_mfma_f32_16x16x32_bf16 v[72:75], v[170:173], v[194:197], v[72:75]
	v_mfma_f32_16x16x32_bf16 v[64:67], v[166:169], v[198:201], v[64:67]
	v_mfma_f32_16x16x32_bf16 v[64:67], v[170:173], v[202:205], v[64:67]
	v_mfma_f32_16x16x32_bf16 v[68:71], v[158:161], v[198:201], v[68:71]
	v_mfma_f32_16x16x32_bf16 v[68:71], v[162:165], v[202:205], v[68:71]
	v_mfma_f32_16x16x32_bf16 v[96:99], v[146:149], v[198:201], v[96:99]
	v_mfma_f32_16x16x32_bf16 v[96:99], v[154:157], v[202:205], v[96:99]
	v_mfma_f32_16x16x32_bf16 v[104:107], v[146:149], v[190:193], v[104:107]
	v_mfma_f32_16x16x32_bf16 v[104:107], v[154:157], v[194:197], v[104:107]
	s_setprio 2
	s_barrier
	v_mfma_f32_16x16x32_bf16 v[108:111], v[128:131], v[190:193], v[108:111]
	v_mfma_f32_16x16x32_bf16 v[108:111], v[142:145], v[194:197], v[108:111]
	v_mfma_f32_16x16x32_bf16 v[100:103], v[128:131], v[198:201], v[100:103]
	v_mfma_f32_16x16x32_bf16 v[100:103], v[142:145], v[202:205], v[100:103]
	s_setprio 0
	s_add_i32 s50, s72, s14
	s_mov_b32 m0, s50
	ds_read_b128 v[174:177], v153 offset:16384
	ds_read_b128 v[178:181], v153 offset:17408
	ds_read_b128 v[182:185], v153 offset:18432
	ds_read_b128 v[186:189], v153 offset:19456
	ds_read_b128 v[190:193], v153 offset:20480
	ds_read_b128 v[194:197], v153 offset:21504
	ds_read_b128 v[198:201], v153 offset:22528
	ds_read_b128 v[202:205], v153 offset:23552
	global_load_lds_dwordx4 v134, s[78:79]
	s_add_i32 m0, s50, 0x2000
	s_add_i32 s50, s73, s14
	s_add_u32 s98, s78, s6
	s_addc_u32 s99, s79, s7
	global_load_lds_dwordx4 v134, s[98:99]
	s_mov_b32 m0, s50
	s_nop 0
	s_add_u32 s98, s78, s8
	s_addc_u32 s99, s79, s9
	global_load_lds_dwordx4 v134, s[98:99]
	s_add_i32 m0, s50, 0x2000
	s_nop 0
	s_add_u32 s98, s78, s10
	s_addc_u32 s99, s79, s11
	global_load_lds_dwordx4 v134, s[98:99]
	s_mov_b32 m0, s20
	s_nop 0
	global_load_lds_dwordx4 v132, s[76:77]
	s_mov_b32 m0, s21
	s_nop 0
	s_add_u32 s98, s76, s6
	s_addc_u32 s99, s77, s7
	global_load_lds_dwordx4 v132, s[98:99]
	s_waitcnt vmcnt(8)
	s_waitcnt lgkmcnt(0)
	s_barrier
	s_setprio 1
	s_waitcnt lgkmcnt(0)
	v_mfma_f32_16x16x32_bf16 v[60:63], v[128:131], v[174:177], v[60:63]
	v_mfma_f32_16x16x32_bf16 v[60:63], v[142:145], v[178:181], v[60:63]
	v_mfma_f32_16x16x32_bf16 v[52:55], v[128:131], v[182:185], v[52:55]
	v_mfma_f32_16x16x32_bf16 v[52:55], v[142:145], v[186:189], v[52:55]
	v_mfma_f32_16x16x32_bf16 v[48:51], v[146:149], v[182:185], v[48:51]
	v_mfma_f32_16x16x32_bf16 v[48:51], v[154:157], v[186:189], v[48:51]
	v_mfma_f32_16x16x32_bf16 v[56:59], v[146:149], v[174:177], v[56:59]
	v_mfma_f32_16x16x32_bf16 v[56:59], v[154:157], v[178:181], v[56:59]
	v_mfma_f32_16x16x32_bf16 v[28:31], v[158:161], v[174:177], v[28:31]
	v_mfma_f32_16x16x32_bf16 v[28:31], v[162:165], v[178:181], v[28:31]
	v_mfma_f32_16x16x32_bf16 v[24:27], v[166:169], v[174:177], v[24:27]
	v_mfma_f32_16x16x32_bf16 v[24:27], v[170:173], v[178:181], v[24:27]
	v_mfma_f32_16x16x32_bf16 v[16:19], v[166:169], v[182:185], v[16:19]
	v_mfma_f32_16x16x32_bf16 v[16:19], v[170:173], v[186:189], v[16:19]
	v_mfma_f32_16x16x32_bf16 v[20:23], v[158:161], v[182:185], v[20:23]
	v_mfma_f32_16x16x32_bf16 v[20:23], v[162:165], v[186:189], v[20:23]
	s_setprio 0
	s_setprio 1
	v_mfma_f32_16x16x32_bf16 v[12:15], v[158:161], v[190:193], v[12:15]
	v_mfma_f32_16x16x32_bf16 v[12:15], v[162:165], v[194:197], v[12:15]
	v_mfma_f32_16x16x32_bf16 v[8:11], v[166:169], v[190:193], v[8:11]
	v_mfma_f32_16x16x32_bf16 v[8:11], v[170:173], v[194:197], v[8:11]
	v_mfma_f32_16x16x32_bf16 v[0:3], v[166:169], v[198:201], v[0:3]
	v_mfma_f32_16x16x32_bf16 v[0:3], v[170:173], v[202:205], v[0:3]
	v_mfma_f32_16x16x32_bf16 v[4:7], v[158:161], v[198:201], v[4:7]
	v_mfma_f32_16x16x32_bf16 v[4:7], v[162:165], v[202:205], v[4:7]
	v_mfma_f32_16x16x32_bf16 v[32:35], v[146:149], v[198:201], v[32:35]
	v_mfma_f32_16x16x32_bf16 v[32:35], v[154:157], v[202:205], v[32:35]
	v_mfma_f32_16x16x32_bf16 v[40:43], v[146:149], v[190:193], v[40:43]
	v_mfma_f32_16x16x32_bf16 v[40:43], v[154:157], v[194:197], v[40:43]
	s_setprio 2
	s_barrier
	v_mfma_f32_16x16x32_bf16 v[44:47], v[128:131], v[190:193], v[44:47]
	v_mfma_f32_16x16x32_bf16 v[44:47], v[142:145], v[194:197], v[44:47]
	v_mfma_f32_16x16x32_bf16 v[36:39], v[128:131], v[198:201], v[36:39]
	v_mfma_f32_16x16x32_bf16 v[36:39], v[142:145], v[202:205], v[36:39]
	s_setprio 0
	s_add_i32 s50, 0, 0x18000
	s_add_i32 s51, 0, 0x1c000
	v_add_u32_e32 v154, s50, v150
	v_add_u32_e32 v170, s51, v150
	ds_read_b128 v[128:131], v154
	ds_read_b128 v[142:145], v154 offset:1024
	ds_read_b128 v[146:149], v154 offset:2048
	ds_read_b128 v[154:157], v154 offset:3072
	ds_read_b128 v[158:161], v170
	ds_read_b128 v[162:165], v170 offset:1024
	ds_read_b128 v[166:169], v170 offset:2048
	ds_read_b128 v[170:173], v170 offset:3072
	s_mov_b32 m0, s33
	ds_read_b128 v[174:177], v153 offset:32768
	ds_read_b128 v[178:181], v153 offset:33792
	ds_read_b128 v[182:185], v153 offset:34816
	ds_read_b128 v[186:189], v153 offset:35840
	ds_read_b128 v[190:193], v153 offset:36864
	ds_read_b128 v[194:197], v153 offset:37888
	ds_read_b128 v[198:201], v153 offset:38912
	ds_read_b128 v[202:205], v153 offset:39936
	s_add_u32 s98, s76, s8
	s_addc_u32 s99, s77, s9
	global_load_lds_dwordx4 v132, s[98:99]
	s_mov_b32 m0, s64
	s_nop 0
	s_add_u32 s98, s76, s10
	s_addc_u32 s99, s77, s11
	global_load_lds_dwordx4 v132, s[98:99]
	s_waitcnt vmcnt(8)
	s_waitcnt lgkmcnt(0)
	s_barrier
	s_setprio 1
	s_waitcnt lgkmcnt(0)
	v_mfma_f32_16x16x32_bf16 v[124:127], v[128:131], v[174:177], v[124:127]
	v_mfma_f32_16x16x32_bf16 v[124:127], v[142:145], v[178:181], v[124:127]
	v_mfma_f32_16x16x32_bf16 v[116:119], v[128:131], v[182:185], v[116:119]
	v_mfma_f32_16x16x32_bf16 v[116:119], v[142:145], v[186:189], v[116:119]
	v_mfma_f32_16x16x32_bf16 v[112:115], v[146:149], v[182:185], v[112:115]
	v_mfma_f32_16x16x32_bf16 v[112:115], v[154:157], v[186:189], v[112:115]
	v_mfma_f32_16x16x32_bf16 v[120:123], v[146:149], v[174:177], v[120:123]
	v_mfma_f32_16x16x32_bf16 v[120:123], v[154:157], v[178:181], v[120:123]
	v_mfma_f32_16x16x32_bf16 v[92:95], v[158:161], v[174:177], v[92:95]
	v_mfma_f32_16x16x32_bf16 v[92:95], v[162:165], v[178:181], v[92:95]
	v_mfma_f32_16x16x32_bf16 v[88:91], v[166:169], v[174:177], v[88:91]
	v_mfma_f32_16x16x32_bf16 v[88:91], v[170:173], v[178:181], v[88:91]
	v_mfma_f32_16x16x32_bf16 v[80:83], v[166:169], v[182:185], v[80:83]
	v_mfma_f32_16x16x32_bf16 v[80:83], v[170:173], v[186:189], v[80:83]
	v_mfma_f32_16x16x32_bf16 v[84:87], v[158:161], v[182:185], v[84:87]
	v_mfma_f32_16x16x32_bf16 v[84:87], v[162:165], v[186:189], v[84:87]
	s_setprio 0
	s_setprio 1
	v_mfma_f32_16x16x32_bf16 v[76:79], v[158:161], v[190:193], v[76:79]
	v_mfma_f32_16x16x32_bf16 v[76:79], v[162:165], v[194:197], v[76:79]
	v_mfma_f32_16x16x32_bf16 v[72:75], v[166:169], v[190:193], v[72:75]
	v_mfma_f32_16x16x32_bf16 v[72:75], v[170:173], v[194:197], v[72:75]
	v_mfma_f32_16x16x32_bf16 v[64:67], v[166:169], v[198:201], v[64:67]
	v_mfma_f32_16x16x32_bf16 v[64:67], v[170:173], v[202:205], v[64:67]
	v_mfma_f32_16x16x32_bf16 v[68:71], v[158:161], v[198:201], v[68:71]
	v_mfma_f32_16x16x32_bf16 v[68:71], v[162:165], v[202:205], v[68:71]
	v_mfma_f32_16x16x32_bf16 v[96:99], v[146:149], v[198:201], v[96:99]
	v_mfma_f32_16x16x32_bf16 v[96:99], v[154:157], v[202:205], v[96:99]
	v_mfma_f32_16x16x32_bf16 v[104:107], v[146:149], v[190:193], v[104:107]
	v_mfma_f32_16x16x32_bf16 v[104:107], v[154:157], v[194:197], v[104:107]
	s_setprio 2
	s_barrier
	v_mfma_f32_16x16x32_bf16 v[108:111], v[128:131], v[190:193], v[108:111]
	v_mfma_f32_16x16x32_bf16 v[108:111], v[142:145], v[194:197], v[108:111]
	v_mfma_f32_16x16x32_bf16 v[100:103], v[128:131], v[198:201], v[100:103]
	v_mfma_f32_16x16x32_bf16 v[100:103], v[142:145], v[202:205], v[100:103]
	s_setprio 0
	s_add_i32 s50, s50, s14
	s_mov_b32 m0, s50
	ds_read_b128 v[174:177], v153 offset:49152
	ds_read_b128 v[178:181], v153 offset:50176
	ds_read_b128 v[182:185], v153 offset:51200
	ds_read_b128 v[186:189], v153 offset:52224
	ds_read_b128 v[190:193], v153 offset:53248
	ds_read_b128 v[194:197], v153 offset:54272
	ds_read_b128 v[198:201], v153 offset:55296
	ds_read_b128 v[202:205], v153 offset:56320
	s_add_u32 s98, s78, s24
	s_addc_u32 s99, s79, s25
	global_load_lds_dwordx4 v134, s[98:99]
	s_add_i32 m0, s50, 0x2000
	s_add_i32 s50, s51, s14
	s_add_u32 s98, s78, s34
	s_addc_u32 s99, s79, s35
	global_load_lds_dwordx4 v134, s[98:99]
	s_mov_b32 m0, s50
	s_add_u32 s98, s78, s36
	s_addc_u32 s99, s79, s37
	global_load_lds_dwordx4 v134, s[98:99]
	s_add_i32 m0, s50, 0x2000
	s_nop 0
	s_add_u32 s98, s78, s38
	s_addc_u32 s99, s79, s39
	global_load_lds_dwordx4 v134, s[98:99]
	s_mov_b32 m0, s66
	s_nop 0
	s_add_u32 s98, s76, s24
	s_addc_u32 s99, s77, s25
	global_load_lds_dwordx4 v132, s[98:99]
	s_mov_b32 m0, s67
	s_nop 0
	s_add_u32 s98, s76, s34
	s_addc_u32 s99, s77, s35
	global_load_lds_dwordx4 v132, s[98:99]
	s_waitcnt vmcnt(8)
	s_waitcnt lgkmcnt(0)
	s_barrier
	s_setprio 1
	s_waitcnt lgkmcnt(0)
	v_mfma_f32_16x16x32_bf16 v[60:63], v[128:131], v[174:177], v[60:63]
	v_mfma_f32_16x16x32_bf16 v[60:63], v[142:145], v[178:181], v[60:63]
	v_mfma_f32_16x16x32_bf16 v[52:55], v[128:131], v[182:185], v[52:55]
	v_mfma_f32_16x16x32_bf16 v[52:55], v[142:145], v[186:189], v[52:55]
	v_mfma_f32_16x16x32_bf16 v[48:51], v[146:149], v[182:185], v[48:51]
	v_mfma_f32_16x16x32_bf16 v[48:51], v[154:157], v[186:189], v[48:51]
	v_mfma_f32_16x16x32_bf16 v[56:59], v[146:149], v[174:177], v[56:59]
	v_mfma_f32_16x16x32_bf16 v[56:59], v[154:157], v[178:181], v[56:59]
	v_mfma_f32_16x16x32_bf16 v[28:31], v[158:161], v[174:177], v[28:31]
	v_mfma_f32_16x16x32_bf16 v[28:31], v[162:165], v[178:181], v[28:31]
	v_mfma_f32_16x16x32_bf16 v[24:27], v[166:169], v[174:177], v[24:27]
	v_mfma_f32_16x16x32_bf16 v[24:27], v[170:173], v[178:181], v[24:27]
	v_mfma_f32_16x16x32_bf16 v[16:19], v[166:169], v[182:185], v[16:19]
	v_mfma_f32_16x16x32_bf16 v[16:19], v[170:173], v[186:189], v[16:19]
	v_mfma_f32_16x16x32_bf16 v[20:23], v[158:161], v[182:185], v[20:23]
	v_mfma_f32_16x16x32_bf16 v[20:23], v[162:165], v[186:189], v[20:23]
	s_setprio 0
	s_setprio 1
	v_mfma_f32_16x16x32_bf16 v[12:15], v[158:161], v[190:193], v[12:15]
	v_mfma_f32_16x16x32_bf16 v[12:15], v[162:165], v[194:197], v[12:15]
	v_mfma_f32_16x16x32_bf16 v[8:11], v[166:169], v[190:193], v[8:11]
	v_mfma_f32_16x16x32_bf16 v[8:11], v[170:173], v[194:197], v[8:11]
	v_mfma_f32_16x16x32_bf16 v[0:3], v[166:169], v[198:201], v[0:3]
	v_mfma_f32_16x16x32_bf16 v[0:3], v[170:173], v[202:205], v[0:3]
	v_mfma_f32_16x16x32_bf16 v[4:7], v[158:161], v[198:201], v[4:7]
	v_mfma_f32_16x16x32_bf16 v[4:7], v[162:165], v[202:205], v[4:7]
	v_mfma_f32_16x16x32_bf16 v[32:35], v[146:149], v[198:201], v[32:35]
	v_mfma_f32_16x16x32_bf16 v[32:35], v[154:157], v[202:205], v[32:35]
	v_mfma_f32_16x16x32_bf16 v[40:43], v[146:149], v[190:193], v[40:43]
	v_mfma_f32_16x16x32_bf16 v[40:43], v[154:157], v[194:197], v[40:43]
	s_setprio 2
	s_barrier
	v_mfma_f32_16x16x32_bf16 v[44:47], v[128:131], v[190:193], v[44:47]
	v_mfma_f32_16x16x32_bf16 v[44:47], v[142:145], v[194:197], v[44:47]
	v_mfma_f32_16x16x32_bf16 v[36:39], v[128:131], v[198:201], v[36:39]
	v_mfma_f32_16x16x32_bf16 v[36:39], v[142:145], v[202:205], v[36:39]
	s_setprio 0
	s_add_i32 s62, s62, 2
	s_add_u32 s74, s74, 0x100
	s_addc_u32 s75, s75, 0
	s_add_u32 s60, s60, 0x100
	s_addc_u32 s61, s61, 0
	s_cmp_gt_u32 s62, 61
	s_cbranch_scc0 .LBB0_627
	s_and_b64 vcc, exec, s[40:41]
	s_cbranch_vccz .LBB0_630
	s_barrier

.Lcm4_skip:
.LBB0_800:
	ds_read_b128 v[128:131], v187
	ds_read_b128 v[132:135], v187 offset:1024
	ds_read_b128 v[136:139], v187 offset:2048
	ds_read_b128 v[140:143], v187 offset:3072
	ds_read_b128 v[144:147], v188
	ds_read_b128 v[148:151], v188 offset:1024
	ds_read_b128 v[152:155], v188 offset:2048
	ds_read_b128 v[156:159], v188 offset:3072
	s_add_u32 s9, s6, 0xfff80080
	s_addc_u32 s50, s7, -1
	s_cmp_eq_u32 s8, 28
	s_cselect_b32 vcc_hi, s5, s50
	s_cselect_b32 vcc_lo, s10, s9
	s_cselect_b32 s51, s11, s78
	s_cselect_b32 s50, s73, s75
	s_add_i32 m0, s65, 0xc000
	ds_read_b128 v[160:163], v189
	ds_read_b128 v[164:167], v189 offset:1024
	ds_read_b128 v[168:171], v189 offset:2048
	ds_read_b128 v[192:195], v189 offset:3072
	ds_read_b128 v[196:199], v189 offset:4096
	ds_read_b128 v[200:203], v189 offset:5120
	ds_read_b128 v[204:207], v189 offset:6144
	ds_read_b128 v[208:211], v189 offset:7168
	global_load_lds_dwordx4 v178, s[6:7]
	s_add_i32 m0, s65, 0xe000
	s_nop 0
	s_add_u32 s98, s6, s36
	s_addc_u32 s99, s7, s37
	global_load_lds_dwordx4 v178, s[98:99]
	s_waitcnt vmcnt(8)
	s_waitcnt lgkmcnt(0)
	s_barrier
	s_setprio 1
	s_waitcnt lgkmcnt(0)
	v_mfma_i32_16x16x64_i8 v[84:87], v[128:131], v[160:163], v[84:87]
	v_mfma_i32_16x16x64_i8 v[84:87], v[132:135], v[164:167], v[84:87]
	v_mfma_i32_16x16x64_i8 v[88:91], v[128:131], v[168:171], v[88:91]
	v_mfma_i32_16x16x64_i8 v[88:91], v[132:135], v[192:195], v[88:91]
	v_mfma_i32_16x16x64_i8 v[20:23], v[136:139], v[168:171], v[20:23]
	v_mfma_i32_16x16x64_i8 v[20:23], v[140:143], v[192:195], v[20:23]
	v_mfma_i32_16x16x64_i8 v[16:19], v[136:139], v[160:163], v[16:19]
	v_mfma_i32_16x16x64_i8 v[16:19], v[140:143], v[164:167], v[16:19]
	v_mfma_i32_16x16x64_i8 v[124:127], v[144:147], v[160:163], v[124:127]
	v_mfma_i32_16x16x64_i8 v[124:127], v[148:151], v[164:167], v[124:127]
	v_mfma_i32_16x16x64_i8 v[68:71], v[152:155], v[160:163], v[68:71]
	v_mfma_i32_16x16x64_i8 v[68:71], v[156:159], v[164:167], v[68:71]
	v_mfma_i32_16x16x64_i8 v[72:75], v[152:155], v[168:171], v[72:75]
	v_mfma_i32_16x16x64_i8 v[72:75], v[156:159], v[192:195], v[72:75]
	v_mfma_i32_16x16x64_i8 v[120:123], v[144:147], v[168:171], v[120:123]
	v_mfma_i32_16x16x64_i8 v[120:123], v[148:151], v[192:195], v[120:123]
	s_setprio 0
	s_setprio 1
	v_mfma_i32_16x16x64_i8 v[116:119], v[144:147], v[196:199], v[116:119]
	v_mfma_i32_16x16x64_i8 v[116:119], v[148:151], v[200:203], v[116:119]
	v_mfma_i32_16x16x64_i8 v[80:83], v[152:155], v[196:199], v[80:83]
	v_mfma_i32_16x16x64_i8 v[80:83], v[156:159], v[200:203], v[80:83]
	v_mfma_i32_16x16x64_i8 v[60:63], v[152:155], v[204:207], v[60:63]
	v_mfma_i32_16x16x64_i8 v[60:63], v[156:159], v[208:211], v[60:63]
	v_mfma_i32_16x16x64_i8 v[112:115], v[144:147], v[204:207], v[112:115]
	v_mfma_i32_16x16x64_i8 v[112:115], v[148:151], v[208:211], v[112:115]
	v_mfma_i32_16x16x64_i8 v[28:31], v[136:139], v[204:207], v[28:31]
	v_mfma_i32_16x16x64_i8 v[28:31], v[140:143], v[208:211], v[28:31]
	v_mfma_i32_16x16x64_i8 v[24:27], v[136:139], v[196:199], v[24:27]
	v_mfma_i32_16x16x64_i8 v[24:27], v[140:143], v[200:203], v[24:27]
	s_setprio 2
	s_barrier
	v_mfma_i32_16x16x64_i8 v[92:95], v[128:131], v[196:199], v[92:95]
	v_mfma_i32_16x16x64_i8 v[92:95], v[132:135], v[200:203], v[92:95]
	v_mfma_i32_16x16x64_i8 v[96:99], v[128:131], v[204:207], v[96:99]
	v_mfma_i32_16x16x64_i8 v[96:99], v[132:135], v[208:211], v[96:99]
	s_setprio 0
	s_add_i32 s9, s80, s33
	s_mov_b64 s[100:101], s[50:51]
	s_mov_b32 m0, s9
	ds_read_b128 v[160:163], v189 offset:16384
	ds_read_b128 v[164:167], v189 offset:17408
	ds_read_b128 v[168:171], v189 offset:18432
	ds_read_b128 v[192:195], v189 offset:19456
	ds_read_b128 v[196:199], v189 offset:20480
	ds_read_b128 v[200:203], v189 offset:21504
	ds_read_b128 v[204:207], v189 offset:22528
	ds_read_b128 v[208:211], v189 offset:23552
	global_load_lds_dwordx4 v174, s[50:51]
	s_add_i32 m0, s9, 0x2000
	s_add_i32 s9, s81, s33
	s_add_u32 s98, s50, s36
	s_addc_u32 s99, s51, s37
	global_load_lds_dwordx4 v174, s[98:99]
	s_mov_b32 m0, s9
	s_nop 0
	s_add_u32 s98, s50, s38
	s_addc_u32 s99, s51, s39
	global_load_lds_dwordx4 v174, s[98:99]
	s_add_i32 m0, s9, 0x2000
	s_nop 0
	s_add_u32 s98, s50, s40
	s_addc_u32 s99, s51, s41
	global_load_lds_dwordx4 v174, s[98:99]
	s_mov_b32 m0, s65
	s_nop 0
	global_load_lds_dwordx4 v172, vcc
	s_mov_b32 m0, s67
	s_nop 0
	s_add_u32 s98, vcc_lo, s36
	s_addc_u32 s99, vcc_hi, s37
	global_load_lds_dwordx4 v172, s[98:99]
	s_waitcnt vmcnt(8)
	s_waitcnt lgkmcnt(0)
	s_barrier
	s_setprio 1
	s_waitcnt lgkmcnt(0)
	v_mfma_i32_16x16x64_i8 v[48:51], v[128:131], v[160:163], v[48:51]
	v_mfma_i32_16x16x64_i8 v[48:51], v[132:135], v[164:167], v[48:51]
	v_mfma_i32_16x16x64_i8 v[52:55], v[128:131], v[168:171], v[52:55]
	v_mfma_i32_16x16x64_i8 v[52:55], v[132:135], v[192:195], v[52:55]
	v_mfma_i32_16x16x64_i8 v[4:7], v[136:139], v[168:171], v[4:7]
	v_mfma_i32_16x16x64_i8 v[4:7], v[140:143], v[192:195], v[4:7]
	v_mfma_i32_16x16x64_i8 v[0:3], v[136:139], v[160:163], v[0:3]
	v_mfma_i32_16x16x64_i8 v[0:3], v[140:143], v[164:167], v[0:3]
	v_mfma_i32_16x16x64_i8 v[108:111], v[144:147], v[160:163], v[108:111]
	v_mfma_i32_16x16x64_i8 v[108:111], v[148:151], v[164:167], v[108:111]
	v_mfma_i32_16x16x64_i8 v[44:47], v[152:155], v[160:163], v[44:47]
	v_mfma_i32_16x16x64_i8 v[44:47], v[156:159], v[164:167], v[44:47]
	v_mfma_i32_16x16x64_i8 v[40:43], v[152:155], v[168:171], v[40:43]
	v_mfma_i32_16x16x64_i8 v[40:43], v[156:159], v[192:195], v[40:43]
	v_mfma_i32_16x16x64_i8 v[104:107], v[144:147], v[168:171], v[104:107]
	v_mfma_i32_16x16x64_i8 v[104:107], v[148:151], v[192:195], v[104:107]
	s_setprio 0
	s_setprio 1
	v_mfma_i32_16x16x64_i8 v[100:103], v[144:147], v[196:199], v[100:103]
	v_mfma_i32_16x16x64_i8 v[100:103], v[148:151], v[200:203], v[100:103]
	v_mfma_i32_16x16x64_i8 v[32:35], v[152:155], v[196:199], v[32:35]
	v_mfma_i32_16x16x64_i8 v[32:35], v[156:159], v[200:203], v[32:35]
	v_mfma_i32_16x16x64_i8 v[36:39], v[152:155], v[204:207], v[36:39]
	v_mfma_i32_16x16x64_i8 v[36:39], v[156:159], v[208:211], v[36:39]
	v_mfma_i32_16x16x64_i8 v[76:79], v[144:147], v[204:207], v[76:79]
	v_mfma_i32_16x16x64_i8 v[76:79], v[148:151], v[208:211], v[76:79]
	v_mfma_i32_16x16x64_i8 v[12:15], v[136:139], v[204:207], v[12:15]
	v_mfma_i32_16x16x64_i8 v[12:15], v[140:143], v[208:211], v[12:15]
	v_mfma_i32_16x16x64_i8 v[8:11], v[136:139], v[196:199], v[8:11]
	v_mfma_i32_16x16x64_i8 v[8:11], v[140:143], v[200:203], v[8:11]
	s_setprio 2
	s_barrier
	v_mfma_i32_16x16x64_i8 v[56:59], v[128:131], v[196:199], v[56:59]
	v_mfma_i32_16x16x64_i8 v[56:59], v[132:135], v[200:203], v[56:59]
	v_mfma_i32_16x16x64_i8 v[64:67], v[128:131], v[204:207], v[64:67]
	v_mfma_i32_16x16x64_i8 v[64:67], v[132:135], v[208:211], v[64:67]
	s_setprio 0
	s_add_i32 s9, 0, 0x18000
	s_add_i32 s50, 0, 0x1c000
	v_add_u32_e32 v140, s9, v186
	v_add_u32_e32 v156, s50, v186
	ds_read_b128 v[128:131], v140
	ds_read_b128 v[132:135], v140 offset:1024
	ds_read_b128 v[136:139], v140 offset:2048
	ds_read_b128 v[140:143], v140 offset:3072
	ds_read_b128 v[144:147], v156
	ds_read_b128 v[148:151], v156 offset:1024
	ds_read_b128 v[152:155], v156 offset:2048
	ds_read_b128 v[156:159], v156 offset:3072
	s_mov_b32 m0, s71
	ds_read_b128 v[160:163], v189 offset:32768
	ds_read_b128 v[164:167], v189 offset:33792
	ds_read_b128 v[168:171], v189 offset:34816
	ds_read_b128 v[192:195], v189 offset:35840
	ds_read_b128 v[196:199], v189 offset:36864
	ds_read_b128 v[200:203], v189 offset:37888
	ds_read_b128 v[204:207], v189 offset:38912
	ds_read_b128 v[208:211], v189 offset:39936
	s_add_u32 s98, vcc_lo, s38
	s_addc_u32 s99, vcc_hi, s39
	global_load_lds_dwordx4 v172, s[98:99]
	s_mov_b32 m0, s82
	s_nop 0
	s_add_u32 s98, vcc_lo, s40
	s_addc_u32 s99, vcc_hi, s41
	global_load_lds_dwordx4 v172, s[98:99]
	s_waitcnt vmcnt(8)
	s_waitcnt lgkmcnt(0)
	s_barrier
	s_setprio 1
	s_waitcnt lgkmcnt(0)
	v_mfma_i32_16x16x64_i8 v[84:87], v[128:131], v[160:163], v[84:87]
	v_mfma_i32_16x16x64_i8 v[84:87], v[132:135], v[164:167], v[84:87]
	v_mfma_i32_16x16x64_i8 v[88:91], v[128:131], v[168:171], v[88:91]
	v_mfma_i32_16x16x64_i8 v[88:91], v[132:135], v[192:195], v[88:91]
	v_mfma_i32_16x16x64_i8 v[20:23], v[136:139], v[168:171], v[20:23]
	v_mfma_i32_16x16x64_i8 v[20:23], v[140:143], v[192:195], v[20:23]
	v_mfma_i32_16x16x64_i8 v[16:19], v[136:139], v[160:163], v[16:19]
	v_mfma_i32_16x16x64_i8 v[16:19], v[140:143], v[164:167], v[16:19]
	v_mfma_i32_16x16x64_i8 v[124:127], v[144:147], v[160:163], v[124:127]
	v_mfma_i32_16x16x64_i8 v[124:127], v[148:151], v[164:167], v[124:127]
	v_mfma_i32_16x16x64_i8 v[68:71], v[152:155], v[160:163], v[68:71]
	v_mfma_i32_16x16x64_i8 v[68:71], v[156:159], v[164:167], v[68:71]
	v_mfma_i32_16x16x64_i8 v[72:75], v[152:155], v[168:171], v[72:75]
	v_mfma_i32_16x16x64_i8 v[72:75], v[156:159], v[192:195], v[72:75]
	v_mfma_i32_16x16x64_i8 v[120:123], v[144:147], v[168:171], v[120:123]
	v_mfma_i32_16x16x64_i8 v[120:123], v[148:151], v[192:195], v[120:123]
	s_setprio 0
	s_setprio 1
	v_mfma_i32_16x16x64_i8 v[116:119], v[144:147], v[196:199], v[116:119]
	v_mfma_i32_16x16x64_i8 v[116:119], v[148:151], v[200:203], v[116:119]
	v_mfma_i32_16x16x64_i8 v[80:83], v[152:155], v[196:199], v[80:83]
	v_mfma_i32_16x16x64_i8 v[80:83], v[156:159], v[200:203], v[80:83]
	v_mfma_i32_16x16x64_i8 v[60:63], v[152:155], v[204:207], v[60:63]
	v_mfma_i32_16x16x64_i8 v[60:63], v[156:159], v[208:211], v[60:63]
	v_mfma_i32_16x16x64_i8 v[112:115], v[144:147], v[204:207], v[112:115]
	v_mfma_i32_16x16x64_i8 v[112:115], v[148:151], v[208:211], v[112:115]
	v_mfma_i32_16x16x64_i8 v[28:31], v[136:139], v[204:207], v[28:31]
	v_mfma_i32_16x16x64_i8 v[28:31], v[140:143], v[208:211], v[28:31]
	v_mfma_i32_16x16x64_i8 v[24:27], v[136:139], v[196:199], v[24:27]
	v_mfma_i32_16x16x64_i8 v[24:27], v[140:143], v[200:203], v[24:27]
	s_setprio 2
	s_barrier
	v_mfma_i32_16x16x64_i8 v[92:95], v[128:131], v[196:199], v[92:95]
	v_mfma_i32_16x16x64_i8 v[92:95], v[132:135], v[200:203], v[92:95]
	v_mfma_i32_16x16x64_i8 v[96:99], v[128:131], v[204:207], v[96:99]
	v_mfma_i32_16x16x64_i8 v[96:99], v[132:135], v[208:211], v[96:99]
	s_setprio 0
	s_add_i32 s9, s9, s33
	s_mov_b32 m0, s9
	ds_read_b128 v[160:163], v189 offset:49152
	ds_read_b128 v[164:167], v189 offset:50176
	ds_read_b128 v[168:171], v189 offset:51200
	ds_read_b128 v[192:195], v189 offset:52224
	ds_read_b128 v[196:199], v189 offset:53248
	ds_read_b128 v[200:203], v189 offset:54272
	ds_read_b128 v[204:207], v189 offset:55296
	ds_read_b128 v[208:211], v189 offset:56320
	s_add_u32 s98, s100, s44
	s_addc_u32 s99, s101, s45
	global_load_lds_dwordx4 v174, s[98:99]
	s_add_i32 m0, s9, 0x2000
	s_add_i32 s9, s50, s33
	s_add_u32 s98, s100, s46
	s_addc_u32 s99, s101, s47
	global_load_lds_dwordx4 v174, s[98:99]
	s_mov_b32 m0, s9
	s_add_u32 s98, s100, s48
	s_addc_u32 s99, s101, s49
	global_load_lds_dwordx4 v174, s[98:99]
	s_add_i32 m0, s9, 0x2000
	s_nop 0
	s_add_u32 s98, s100, s52
	s_addc_u32 s99, s101, s53
	global_load_lds_dwordx4 v174, s[98:99]
	s_mov_b32 m0, s90
	s_nop 0
	s_add_u32 s98, vcc_lo, s44
	s_addc_u32 s99, vcc_hi, s45
	global_load_lds_dwordx4 v172, s[98:99]
	s_mov_b32 m0, s91
	s_nop 0
	s_add_u32 s98, vcc_lo, s46
	s_addc_u32 s99, vcc_hi, s47
	global_load_lds_dwordx4 v172, s[98:99]
	s_waitcnt vmcnt(8)
	s_waitcnt lgkmcnt(0)
	s_barrier
	s_setprio 1
	s_waitcnt lgkmcnt(0)
	v_mfma_i32_16x16x64_i8 v[48:51], v[128:131], v[160:163], v[48:51]
	v_mfma_i32_16x16x64_i8 v[48:51], v[132:135], v[164:167], v[48:51]
	v_mfma_i32_16x16x64_i8 v[52:55], v[128:131], v[168:171], v[52:55]
	v_mfma_i32_16x16x64_i8 v[52:55], v[132:135], v[192:195], v[52:55]
	v_mfma_i32_16x16x64_i8 v[4:7], v[136:139], v[168:171], v[4:7]
	v_mfma_i32_16x16x64_i8 v[4:7], v[140:143], v[192:195], v[4:7]
	v_mfma_i32_16x16x64_i8 v[0:3], v[136:139], v[160:163], v[0:3]
	v_mfma_i32_16x16x64_i8 v[0:3], v[140:143], v[164:167], v[0:3]
	v_mfma_i32_16x16x64_i8 v[108:111], v[144:147], v[160:163], v[108:111]
	v_mfma_i32_16x16x64_i8 v[108:111], v[148:151], v[164:167], v[108:111]
	v_mfma_i32_16x16x64_i8 v[44:47], v[152:155], v[160:163], v[44:47]
	v_mfma_i32_16x16x64_i8 v[44:47], v[156:159], v[164:167], v[44:47]
	v_mfma_i32_16x16x64_i8 v[40:43], v[152:155], v[168:171], v[40:43]
	v_mfma_i32_16x16x64_i8 v[40:43], v[156:159], v[192:195], v[40:43]
	v_mfma_i32_16x16x64_i8 v[104:107], v[144:147], v[168:171], v[104:107]
	v_mfma_i32_16x16x64_i8 v[104:107], v[148:151], v[192:195], v[104:107]
	s_setprio 0
	s_setprio 1
	v_mfma_i32_16x16x64_i8 v[100:103], v[144:147], v[196:199], v[100:103]
	v_mfma_i32_16x16x64_i8 v[100:103], v[148:151], v[200:203], v[100:103]
	v_mfma_i32_16x16x64_i8 v[32:35], v[152:155], v[196:199], v[32:35]
	v_mfma_i32_16x16x64_i8 v[32:35], v[156:159], v[200:203], v[32:35]
	v_mfma_i32_16x16x64_i8 v[36:39], v[152:155], v[204:207], v[36:39]
	v_mfma_i32_16x16x64_i8 v[36:39], v[156:159], v[208:211], v[36:39]
	v_mfma_i32_16x16x64_i8 v[76:79], v[144:147], v[204:207], v[76:79]
	v_mfma_i32_16x16x64_i8 v[76:79], v[148:151], v[208:211], v[76:79]
	v_mfma_i32_16x16x64_i8 v[12:15], v[136:139], v[204:207], v[12:15]
	v_mfma_i32_16x16x64_i8 v[12:15], v[140:143], v[208:211], v[12:15]
	v_mfma_i32_16x16x64_i8 v[8:11], v[136:139], v[196:199], v[8:11]
	v_mfma_i32_16x16x64_i8 v[8:11], v[140:143], v[200:203], v[8:11]
	s_setprio 2
	s_barrier
	v_mfma_i32_16x16x64_i8 v[56:59], v[128:131], v[196:199], v[56:59]
	v_mfma_i32_16x16x64_i8 v[56:59], v[132:135], v[200:203], v[56:59]
	v_mfma_i32_16x16x64_i8 v[64:67], v[128:131], v[204:207], v[64:67]
	v_mfma_i32_16x16x64_i8 v[64:67], v[132:135], v[208:211], v[64:67]
	s_setprio 0
	s_add_i32 s8, s8, 2
	s_add_u32 s75, s75, 0x100
	s_addc_u32 s78, s78, 0
	s_add_u32 s6, s6, 0x100
	s_addc_u32 s7, s7, 0
	s_cmp_gt_u32 s8, 29
	s_cbranch_scc0 .LBB0_800
	s_and_b64 vcc, exec, s[54:55]
	s_cbranch_vccz .LBB0_803
	s_barrier

.LBB0_1034:
	ds_read_b128 v[138:141], v151
	ds_read_b128 v[142:145], v151 offset:1024
	ds_read_b128 v[146:149], v151 offset:2048
	ds_read_b128 v[154:157], v151 offset:3072
	ds_read_b128 v[158:161], v152
	ds_read_b128 v[162:165], v152 offset:1024
	ds_read_b128 v[166:169], v152 offset:2048
	ds_read_b128 v[170:173], v152 offset:3072
	s_add_u32 s47, s44, 0xffd50080
	s_addc_u32 s64, s45, -1
	s_cmpk_eq_i32 s46, 0xa8
	s_cselect_b32 s65, s5, s64
	s_cselect_b32 s64, s4, s47
	s_cselect_b32 s67, s43, s63
	s_cselect_b32 s66, s42, s62
	s_add_i32 m0, s25, 0xc000
	ds_read_b128 v[174:177], v153
	ds_read_b128 v[178:181], v153 offset:1024
	ds_read_b128 v[182:185], v153 offset:2048
	ds_read_b128 v[186:189], v153 offset:3072
	ds_read_b128 v[190:193], v153 offset:4096
	ds_read_b128 v[194:197], v153 offset:5120
	ds_read_b128 v[198:201], v153 offset:6144
	ds_read_b128 v[202:205], v153 offset:7168
	global_load_lds_dwordx4 v132, s[44:45]
	s_add_i32 m0, s25, 0xe000
	s_nop 0
	s_add_u32 s98, s44, s0
	s_addc_u32 s99, s45, s1
	global_load_lds_dwordx4 v132, s[98:99]
	s_waitcnt vmcnt(8)
	s_waitcnt lgkmcnt(0)
	s_barrier
	s_setprio 1
	s_waitcnt lgkmcnt(0)
	v_mfma_f32_16x16x32_bf16 v[124:127], v[138:141], v[174:177], v[124:127]
	v_mfma_f32_16x16x32_bf16 v[124:127], v[142:145], v[178:181], v[124:127]
	v_mfma_f32_16x16x32_bf16 v[116:119], v[138:141], v[182:185], v[116:119]
	v_mfma_f32_16x16x32_bf16 v[116:119], v[142:145], v[186:189], v[116:119]
	v_mfma_f32_16x16x32_bf16 v[112:115], v[146:149], v[182:185], v[112:115]
	v_mfma_f32_16x16x32_bf16 v[112:115], v[154:157], v[186:189], v[112:115]
	v_mfma_f32_16x16x32_bf16 v[120:123], v[146:149], v[174:177], v[120:123]
	v_mfma_f32_16x16x32_bf16 v[120:123], v[154:157], v[178:181], v[120:123]
	v_mfma_f32_16x16x32_bf16 v[92:95], v[158:161], v[174:177], v[92:95]
	v_mfma_f32_16x16x32_bf16 v[92:95], v[162:165], v[178:181], v[92:95]
	v_mfma_f32_16x16x32_bf16 v[88:91], v[166:169], v[174:177], v[88:91]
	v_mfma_f32_16x16x32_bf16 v[88:91], v[170:173], v[178:181], v[88:91]
	v_mfma_f32_16x16x32_bf16 v[80:83], v[166:169], v[182:185], v[80:83]
	v_mfma_f32_16x16x32_bf16 v[80:83], v[170:173], v[186:189], v[80:83]
	v_mfma_f32_16x16x32_bf16 v[84:87], v[158:161], v[182:185], v[84:87]
	v_mfma_f32_16x16x32_bf16 v[84:87], v[162:165], v[186:189], v[84:87]
	s_setprio 0
	s_setprio 1
	v_mfma_f32_16x16x32_bf16 v[76:79], v[158:161], v[190:193], v[76:79]
	v_mfma_f32_16x16x32_bf16 v[76:79], v[162:165], v[194:197], v[76:79]
	v_mfma_f32_16x16x32_bf16 v[72:75], v[166:169], v[190:193], v[72:75]
	v_mfma_f32_16x16x32_bf16 v[72:75], v[170:173], v[194:197], v[72:75]
	v_mfma_f32_16x16x32_bf16 v[64:67], v[166:169], v[198:201], v[64:67]
	v_mfma_f32_16x16x32_bf16 v[64:67], v[170:173], v[202:205], v[64:67]
	v_mfma_f32_16x16x32_bf16 v[68:71], v[158:161], v[198:201], v[68:71]
	v_mfma_f32_16x16x32_bf16 v[68:71], v[162:165], v[202:205], v[68:71]
	v_mfma_f32_16x16x32_bf16 v[96:99], v[146:149], v[198:201], v[96:99]
	v_mfma_f32_16x16x32_bf16 v[96:99], v[154:157], v[202:205], v[96:99]
	v_mfma_f32_16x16x32_bf16 v[104:107], v[146:149], v[190:193], v[104:107]
	v_mfma_f32_16x16x32_bf16 v[104:107], v[154:157], v[194:197], v[104:107]
	s_setprio 2
	s_barrier
	v_mfma_f32_16x16x32_bf16 v[108:111], v[138:141], v[190:193], v[108:111]
	v_mfma_f32_16x16x32_bf16 v[108:111], v[142:145], v[194:197], v[108:111]
	v_mfma_f32_16x16x32_bf16 v[100:103], v[138:141], v[198:201], v[100:103]
	v_mfma_f32_16x16x32_bf16 v[100:103], v[142:145], v[202:205], v[100:103]
	s_setprio 0
	s_add_i32 s47, s56, s24
	s_mov_b32 m0, s47
	ds_read_b128 v[174:177], v153 offset:16384
	ds_read_b128 v[178:181], v153 offset:17408
	ds_read_b128 v[182:185], v153 offset:18432
	ds_read_b128 v[186:189], v153 offset:19456
	ds_read_b128 v[190:193], v153 offset:20480
	ds_read_b128 v[194:197], v153 offset:21504
	ds_read_b128 v[198:201], v153 offset:22528
	ds_read_b128 v[202:205], v153 offset:23552
	global_load_lds_dwordx4 v130, s[66:67]
	s_add_i32 m0, s47, 0x2000
	s_add_i32 s47, s57, s24
	s_add_u32 s98, s66, s0
	s_addc_u32 s99, s67, s1
	global_load_lds_dwordx4 v130, s[98:99]
	s_mov_b32 m0, s47
	s_nop 0
	s_add_u32 s98, s66, s6
	s_addc_u32 s99, s67, s7
	global_load_lds_dwordx4 v130, s[98:99]
	s_add_i32 m0, s47, 0x2000
	s_nop 0
	s_add_u32 s98, s66, s8
	s_addc_u32 s99, s67, s9
	global_load_lds_dwordx4 v130, s[98:99]
	s_mov_b64 s[100:101], s[64:65]
	s_mov_b32 m0, s25
	s_nop 0
	global_load_lds_dwordx4 v128, s[64:65]
	s_mov_b32 m0, s33
	s_nop 0
	s_add_u32 s98, s64, s0
	s_addc_u32 s99, s65, s1
	global_load_lds_dwordx4 v128, s[98:99]
	s_waitcnt vmcnt(8)
	s_waitcnt lgkmcnt(0)
	s_barrier
	s_setprio 1
	s_waitcnt lgkmcnt(0)
	v_mfma_f32_16x16x32_bf16 v[60:63], v[138:141], v[174:177], v[60:63]
	v_mfma_f32_16x16x32_bf16 v[60:63], v[142:145], v[178:181], v[60:63]
	v_mfma_f32_16x16x32_bf16 v[52:55], v[138:141], v[182:185], v[52:55]
	v_mfma_f32_16x16x32_bf16 v[52:55], v[142:145], v[186:189], v[52:55]
	v_mfma_f32_16x16x32_bf16 v[48:51], v[146:149], v[182:185], v[48:51]
	v_mfma_f32_16x16x32_bf16 v[48:51], v[154:157], v[186:189], v[48:51]
	v_mfma_f32_16x16x32_bf16 v[56:59], v[146:149], v[174:177], v[56:59]
	v_mfma_f32_16x16x32_bf16 v[56:59], v[154:157], v[178:181], v[56:59]
	v_mfma_f32_16x16x32_bf16 v[28:31], v[158:161], v[174:177], v[28:31]
	v_mfma_f32_16x16x32_bf16 v[28:31], v[162:165], v[178:181], v[28:31]
	v_mfma_f32_16x16x32_bf16 v[24:27], v[166:169], v[174:177], v[24:27]
	v_mfma_f32_16x16x32_bf16 v[24:27], v[170:173], v[178:181], v[24:27]
	v_mfma_f32_16x16x32_bf16 v[16:19], v[166:169], v[182:185], v[16:19]
	v_mfma_f32_16x16x32_bf16 v[16:19], v[170:173], v[186:189], v[16:19]
	v_mfma_f32_16x16x32_bf16 v[20:23], v[158:161], v[182:185], v[20:23]
	v_mfma_f32_16x16x32_bf16 v[20:23], v[162:165], v[186:189], v[20:23]
	s_setprio 0
	s_setprio 1
	v_mfma_f32_16x16x32_bf16 v[12:15], v[158:161], v[190:193], v[12:15]
	v_mfma_f32_16x16x32_bf16 v[12:15], v[162:165], v[194:197], v[12:15]
	v_mfma_f32_16x16x32_bf16 v[8:11], v[166:169], v[190:193], v[8:11]
	v_mfma_f32_16x16x32_bf16 v[8:11], v[170:173], v[194:197], v[8:11]
	v_mfma_f32_16x16x32_bf16 v[0:3], v[166:169], v[198:201], v[0:3]
	v_mfma_f32_16x16x32_bf16 v[0:3], v[170:173], v[202:205], v[0:3]
	v_mfma_f32_16x16x32_bf16 v[4:7], v[158:161], v[198:201], v[4:7]
	v_mfma_f32_16x16x32_bf16 v[4:7], v[162:165], v[202:205], v[4:7]
	v_mfma_f32_16x16x32_bf16 v[32:35], v[146:149], v[198:201], v[32:35]
	v_mfma_f32_16x16x32_bf16 v[32:35], v[154:157], v[202:205], v[32:35]
	v_mfma_f32_16x16x32_bf16 v[40:43], v[146:149], v[190:193], v[40:43]
	v_mfma_f32_16x16x32_bf16 v[40:43], v[154:157], v[194:197], v[40:43]
	s_setprio 2
	s_barrier
	v_mfma_f32_16x16x32_bf16 v[44:47], v[138:141], v[190:193], v[44:47]
	v_mfma_f32_16x16x32_bf16 v[44:47], v[142:145], v[194:197], v[44:47]
	v_mfma_f32_16x16x32_bf16 v[36:39], v[138:141], v[198:201], v[36:39]
	v_mfma_f32_16x16x32_bf16 v[36:39], v[142:145], v[202:205], v[36:39]
	s_setprio 0
	s_add_i32 s47, 0, 0x18000
	s_add_i32 s64, 0, 0x1c000
	v_add_u32_e32 v154, s47, v150
	v_add_u32_e32 v170, s64, v150
	ds_read_b128 v[138:141], v154
	ds_read_b128 v[142:145], v154 offset:1024
	ds_read_b128 v[146:149], v154 offset:2048
	ds_read_b128 v[154:157], v154 offset:3072
	ds_read_b128 v[158:161], v170
	ds_read_b128 v[162:165], v170 offset:1024
	ds_read_b128 v[166:169], v170 offset:2048
	ds_read_b128 v[170:173], v170 offset:3072
	s_mov_b32 m0, s48
	ds_read_b128 v[174:177], v153 offset:32768
	ds_read_b128 v[178:181], v153 offset:33792
	ds_read_b128 v[182:185], v153 offset:34816
	ds_read_b128 v[186:189], v153 offset:35840
	ds_read_b128 v[190:193], v153 offset:36864
	ds_read_b128 v[194:197], v153 offset:37888
	ds_read_b128 v[198:201], v153 offset:38912
	ds_read_b128 v[202:205], v153 offset:39936
	s_add_u32 s98, s100, s6
	s_addc_u32 s99, s101, s7
	global_load_lds_dwordx4 v128, s[98:99]
	s_mov_b32 m0, s49
	s_nop 0
	s_add_u32 s98, s100, s8
	s_addc_u32 s99, s101, s9
	global_load_lds_dwordx4 v128, s[98:99]
	s_waitcnt vmcnt(8)
	s_waitcnt lgkmcnt(0)
	s_barrier
	s_setprio 1
	s_waitcnt lgkmcnt(0)
	v_mfma_f32_16x16x32_bf16 v[124:127], v[138:141], v[174:177], v[124:127]
	v_mfma_f32_16x16x32_bf16 v[124:127], v[142:145], v[178:181], v[124:127]
	v_mfma_f32_16x16x32_bf16 v[116:119], v[138:141], v[182:185], v[116:119]
	v_mfma_f32_16x16x32_bf16 v[116:119], v[142:145], v[186:189], v[116:119]
	v_mfma_f32_16x16x32_bf16 v[112:115], v[146:149], v[182:185], v[112:115]
	v_mfma_f32_16x16x32_bf16 v[112:115], v[154:157], v[186:189], v[112:115]
	v_mfma_f32_16x16x32_bf16 v[120:123], v[146:149], v[174:177], v[120:123]
	v_mfma_f32_16x16x32_bf16 v[120:123], v[154:157], v[178:181], v[120:123]
	v_mfma_f32_16x16x32_bf16 v[92:95], v[158:161], v[174:177], v[92:95]
	v_mfma_f32_16x16x32_bf16 v[92:95], v[162:165], v[178:181], v[92:95]
	v_mfma_f32_16x16x32_bf16 v[88:91], v[166:169], v[174:177], v[88:91]
	v_mfma_f32_16x16x32_bf16 v[88:91], v[170:173], v[178:181], v[88:91]
	v_mfma_f32_16x16x32_bf16 v[80:83], v[166:169], v[182:185], v[80:83]
	v_mfma_f32_16x16x32_bf16 v[80:83], v[170:173], v[186:189], v[80:83]
	v_mfma_f32_16x16x32_bf16 v[84:87], v[158:161], v[182:185], v[84:87]
	v_mfma_f32_16x16x32_bf16 v[84:87], v[162:165], v[186:189], v[84:87]
	s_setprio 0
	s_setprio 1
	v_mfma_f32_16x16x32_bf16 v[76:79], v[158:161], v[190:193], v[76:79]
	v_mfma_f32_16x16x32_bf16 v[76:79], v[162:165], v[194:197], v[76:79]
	v_mfma_f32_16x16x32_bf16 v[72:75], v[166:169], v[190:193], v[72:75]
	v_mfma_f32_16x16x32_bf16 v[72:75], v[170:173], v[194:197], v[72:75]
	v_mfma_f32_16x16x32_bf16 v[64:67], v[166:169], v[198:201], v[64:67]
	v_mfma_f32_16x16x32_bf16 v[64:67], v[170:173], v[202:205], v[64:67]
	v_mfma_f32_16x16x32_bf16 v[68:71], v[158:161], v[198:201], v[68:71]
	v_mfma_f32_16x16x32_bf16 v[68:71], v[162:165], v[202:205], v[68:71]
	v_mfma_f32_16x16x32_bf16 v[96:99], v[146:149], v[198:201], v[96:99]
	v_mfma_f32_16x16x32_bf16 v[96:99], v[154:157], v[202:205], v[96:99]
	v_mfma_f32_16x16x32_bf16 v[104:107], v[146:149], v[190:193], v[104:107]
	v_mfma_f32_16x16x32_bf16 v[104:107], v[154:157], v[194:197], v[104:107]
	s_setprio 2
	s_barrier
	v_mfma_f32_16x16x32_bf16 v[108:111], v[138:141], v[190:193], v[108:111]
	v_mfma_f32_16x16x32_bf16 v[108:111], v[142:145], v[194:197], v[108:111]
	v_mfma_f32_16x16x32_bf16 v[100:103], v[138:141], v[198:201], v[100:103]
	v_mfma_f32_16x16x32_bf16 v[100:103], v[142:145], v[202:205], v[100:103]
	s_setprio 0
	s_add_i32 s47, s47, s24
	s_mov_b32 m0, s47
	ds_read_b128 v[174:177], v153 offset:49152
	ds_read_b128 v[178:181], v153 offset:50176
	ds_read_b128 v[182:185], v153 offset:51200
	ds_read_b128 v[186:189], v153 offset:52224
	ds_read_b128 v[190:193], v153 offset:53248
	ds_read_b128 v[194:197], v153 offset:54272
	ds_read_b128 v[198:201], v153 offset:55296
	ds_read_b128 v[202:205], v153 offset:56320
	s_add_u32 s98, s66, s16
	s_addc_u32 s99, s67, s17
	global_load_lds_dwordx4 v130, s[98:99]
	s_add_i32 m0, s47, 0x2000
	s_add_i32 s47, s64, s24
	s_add_u32 s98, s66, s20
	s_addc_u32 s99, s67, s21
	global_load_lds_dwordx4 v130, s[98:99]
	s_mov_b32 m0, s47
	s_add_u32 s98, s66, s34
	s_addc_u32 s99, s67, s35
	global_load_lds_dwordx4 v130, s[98:99]
	s_add_i32 m0, s47, 0x2000
	s_nop 0
	s_add_u32 s98, s66, s36
	s_addc_u32 s99, s67, s37
	global_load_lds_dwordx4 v130, s[98:99]
	s_mov_b32 m0, s51
	s_nop 0
	s_add_u32 s98, s100, s16
	s_addc_u32 s99, s101, s17
	global_load_lds_dwordx4 v128, s[98:99]
	s_mov_b32 m0, s52
	s_nop 0
	s_add_u32 s98, s100, s20
	s_addc_u32 s99, s101, s21
	global_load_lds_dwordx4 v128, s[98:99]
	s_waitcnt vmcnt(8)
	s_waitcnt lgkmcnt(0)
	s_barrier
	s_setprio 1
	s_waitcnt lgkmcnt(0)
	v_mfma_f32_16x16x32_bf16 v[60:63], v[138:141], v[174:177], v[60:63]
	v_mfma_f32_16x16x32_bf16 v[60:63], v[142:145], v[178:181], v[60:63]
	v_mfma_f32_16x16x32_bf16 v[52:55], v[138:141], v[182:185], v[52:55]
	v_mfma_f32_16x16x32_bf16 v[52:55], v[142:145], v[186:189], v[52:55]
	v_mfma_f32_16x16x32_bf16 v[48:51], v[146:149], v[182:185], v[48:51]
	v_mfma_f32_16x16x32_bf16 v[48:51], v[154:157], v[186:189], v[48:51]
	v_mfma_f32_16x16x32_bf16 v[56:59], v[146:149], v[174:177], v[56:59]
	v_mfma_f32_16x16x32_bf16 v[56:59], v[154:157], v[178:181], v[56:59]
	v_mfma_f32_16x16x32_bf16 v[28:31], v[158:161], v[174:177], v[28:31]
	v_mfma_f32_16x16x32_bf16 v[28:31], v[162:165], v[178:181], v[28:31]
	v_mfma_f32_16x16x32_bf16 v[24:27], v[166:169], v[174:177], v[24:27]
	v_mfma_f32_16x16x32_bf16 v[24:27], v[170:173], v[178:181], v[24:27]
	v_mfma_f32_16x16x32_bf16 v[16:19], v[166:169], v[182:185], v[16:19]
	v_mfma_f32_16x16x32_bf16 v[16:19], v[170:173], v[186:189], v[16:19]
	v_mfma_f32_16x16x32_bf16 v[20:23], v[158:161], v[182:185], v[20:23]
	v_mfma_f32_16x16x32_bf16 v[20:23], v[162:165], v[186:189], v[20:23]
	s_setprio 0
	s_setprio 1
	v_mfma_f32_16x16x32_bf16 v[12:15], v[158:161], v[190:193], v[12:15]
	v_mfma_f32_16x16x32_bf16 v[12:15], v[162:165], v[194:197], v[12:15]
	v_mfma_f32_16x16x32_bf16 v[8:11], v[166:169], v[190:193], v[8:11]
	v_mfma_f32_16x16x32_bf16 v[8:11], v[170:173], v[194:197], v[8:11]
	v_mfma_f32_16x16x32_bf16 v[0:3], v[166:169], v[198:201], v[0:3]
	v_mfma_f32_16x16x32_bf16 v[0:3], v[170:173], v[202:205], v[0:3]
	v_mfma_f32_16x16x32_bf16 v[4:7], v[158:161], v[198:201], v[4:7]
	v_mfma_f32_16x16x32_bf16 v[4:7], v[162:165], v[202:205], v[4:7]
	v_mfma_f32_16x16x32_bf16 v[32:35], v[146:149], v[198:201], v[32:35]
	v_mfma_f32_16x16x32_bf16 v[32:35], v[154:157], v[202:205], v[32:35]
	v_mfma_f32_16x16x32_bf16 v[40:43], v[146:149], v[190:193], v[40:43]
	v_mfma_f32_16x16x32_bf16 v[40:43], v[154:157], v[194:197], v[40:43]
	s_setprio 2
	s_barrier
	v_mfma_f32_16x16x32_bf16 v[44:47], v[138:141], v[190:193], v[44:47]
	v_mfma_f32_16x16x32_bf16 v[44:47], v[142:145], v[194:197], v[44:47]
	v_mfma_f32_16x16x32_bf16 v[36:39], v[138:141], v[198:201], v[36:39]
	v_mfma_f32_16x16x32_bf16 v[36:39], v[142:145], v[202:205], v[36:39]
	s_setprio 0
	s_add_i32 s46, s46, 2
	s_add_u32 s62, s62, 0x100
	s_addc_u32 s63, s63, 0
	s_add_u32 s44, s44, 0x100
	s_addc_u32 s45, s45, 0
	s_cmpk_gt_u32 s46, 0xa9
	s_cbranch_scc0 .LBB0_1034
	s_and_b64 vcc, exec, s[38:39]
	s_cbranch_vccz .LBB0_1037
	s_barrier

.LBB0_1180:
	ds_read_b128 v[112:115], v181
	ds_read_b128 v[116:119], v181 offset:1024
	ds_read_b128 v[128:131], v181 offset:2048
	ds_read_b128 v[142:145], v181 offset:3072
	ds_read_b128 v[146:149], v202
	ds_read_b128 v[150:153], v202 offset:1024
	ds_read_b128 v[154:157], v202 offset:2048
	ds_read_b128 v[168:171], v202 offset:3072
	s_add_u32 s49, s46, 0xfff80080
	s_addc_u32 s70, s47, -1
	s_cmp_eq_u32 s48, 28
	s_cselect_b32 s71, s39, s70
	s_cselect_b32 s70, s66, s49
	s_cselect_b32 s73, s37, s69
	s_cselect_b32 s72, s67, s68
	s_add_i32 m0, s45, 0xc000
	ds_read_b128 v[172:175], v203
	ds_read_b128 v[182:185], v203 offset:1024
	ds_read_b128 v[186:189], v203 offset:2048
	ds_read_b128 v[190:193], v203 offset:3072
	ds_read_b128 v[194:197], v203 offset:4096
	ds_read_b128 v[198:201], v203 offset:5120
	ds_read_b128 v[206:209], v203 offset:6144
	ds_read_b128 v[210:213], v203 offset:7168
	global_load_lds_dwordx4 v162, s[46:47]
	s_add_i32 m0, s45, 0xe000
	s_nop 0
	s_add_u32 s98, s46, s2
	s_addc_u32 s99, s47, s3
	global_load_lds_dwordx4 v162, s[98:99]
	s_waitcnt vmcnt(8)
	s_waitcnt lgkmcnt(0)
	s_barrier
	s_setprio 1
	s_waitcnt lgkmcnt(0)
	v_mfma_i32_16x16x64_i8 v[138:141], v[112:115], v[172:175], v[138:141]
	v_mfma_i32_16x16x64_i8 v[132:135], v[128:131], v[172:175], v[134:137]
	v_mfma_i32_16x16x64_i8 v[124:127], v[112:115], v[186:189], v[124:127]
	v_mfma_i32_16x16x64_i8 v[120:123], v[128:131], v[186:189], v[120:123]
	v_mfma_i32_16x16x64_i8 v[108:111], v[112:115], v[194:197], v[108:111]
	v_mfma_i32_16x16x64_i8 v[104:107], v[128:131], v[194:197], v[104:107]
	v_mfma_i32_16x16x64_i8 v[100:103], v[112:115], v[206:209], v[100:103]
	v_mfma_i32_16x16x64_i8 v[96:99], v[128:131], v[206:209], v[96:99]
	v_mfma_i32_16x16x64_i8 v[138:141], v[116:119], v[182:185], v[138:141]
	v_mfma_i32_16x16x64_i8 v[132:135], v[142:145], v[182:185], v[132:135]
	v_mfma_i32_16x16x64_i8 v[124:127], v[116:119], v[190:193], v[124:127]
	v_mfma_i32_16x16x64_i8 v[120:123], v[142:145], v[190:193], v[120:123]
	v_mfma_i32_16x16x64_i8 v[108:111], v[116:119], v[198:201], v[108:111]
	v_mfma_i32_16x16x64_i8 v[104:107], v[142:145], v[198:201], v[104:107]
	v_mfma_i32_16x16x64_i8 v[100:103], v[116:119], v[210:213], v[100:103]
	v_mfma_i32_16x16x64_i8 v[96:99], v[142:145], v[210:213], v[96:99]
	s_setprio 0
	s_setprio 1
	v_mfma_i32_16x16x64_i8 v[60:63], v[146:149], v[172:175], v[60:63]
	v_mfma_i32_16x16x64_i8 v[60:63], v[150:153], v[182:185], v[60:63]
	v_mfma_i32_16x16x64_i8 v[56:59], v[154:157], v[172:175], v[56:59]
	v_mfma_i32_16x16x64_i8 v[56:59], v[168:171], v[182:185], v[56:59]
	v_mfma_i32_16x16x64_i8 v[52:55], v[146:149], v[186:189], v[52:55]
	v_mfma_i32_16x16x64_i8 v[52:55], v[150:153], v[190:193], v[52:55]
	v_mfma_i32_16x16x64_i8 v[48:51], v[154:157], v[186:189], v[48:51]
	v_mfma_i32_16x16x64_i8 v[48:51], v[168:171], v[190:193], v[48:51]
	v_mfma_i32_16x16x64_i8 v[44:47], v[146:149], v[194:197], v[44:47]
	v_mfma_i32_16x16x64_i8 v[44:47], v[150:153], v[198:201], v[44:47]
	v_mfma_i32_16x16x64_i8 v[40:43], v[154:157], v[194:197], v[40:43]
	v_mfma_i32_16x16x64_i8 v[40:43], v[168:171], v[198:201], v[40:43]
	s_setprio 2
	s_barrier
	v_mfma_i32_16x16x64_i8 v[36:39], v[146:149], v[206:209], v[36:39]
	v_mfma_i32_16x16x64_i8 v[36:39], v[150:153], v[210:213], v[36:39]
	v_mfma_i32_16x16x64_i8 v[32:35], v[154:157], v[206:209], v[32:35]
	v_mfma_i32_16x16x64_i8 v[32:35], v[168:171], v[210:213], v[32:35]
	s_setprio 0
	s_add_i32 s49, s61, s33
	s_mov_b32 m0, s49
	ds_read_b128 v[172:175], v203 offset:16384
	ds_read_b128 v[182:185], v203 offset:17408
	ds_read_b128 v[186:189], v203 offset:18432
	ds_read_b128 v[190:193], v203 offset:19456
	ds_read_b128 v[194:197], v203 offset:20480
	ds_read_b128 v[198:201], v203 offset:21504
	ds_read_b128 v[206:209], v203 offset:22528
	ds_read_b128 v[210:213], v203 offset:23552
	global_load_lds_dwordx4 v160, s[72:73]
	s_add_i32 m0, s49, 0x2000
	s_add_i32 s49, s62, s33
	s_add_u32 s98, s72, s2
	s_addc_u32 s99, s73, s3
	global_load_lds_dwordx4 v160, s[98:99]
	s_mov_b32 m0, s49
	s_mov_b64 s[100:101], s[70:71]
	s_add_u32 s98, s72, s6
	s_addc_u32 s99, s73, s7
	global_load_lds_dwordx4 v160, s[98:99]
	s_add_i32 m0, s49, 0x2000
	s_nop 0
	s_add_u32 s98, s72, s8
	s_addc_u32 s99, s73, s9
	global_load_lds_dwordx4 v160, s[98:99]
	s_mov_b32 m0, s45
	s_nop 0
	global_load_lds_dwordx4 v158, s[70:71]
	s_mov_b32 m0, s50
	s_nop 0
	s_add_u32 s98, s70, s2
	s_addc_u32 s99, s71, s3
	global_load_lds_dwordx4 v158, s[98:99]
	s_waitcnt vmcnt(8)
	s_waitcnt lgkmcnt(0)
	s_barrier
	s_setprio 1
	s_waitcnt lgkmcnt(0)
	v_mfma_i32_16x16x64_i8 v[92:95], v[112:115], v[172:175], v[92:95]
	v_mfma_i32_16x16x64_i8 v[92:95], v[116:119], v[182:185], v[92:95]
	v_mfma_i32_16x16x64_i8 v[84:87], v[112:115], v[186:189], v[84:87]
	v_mfma_i32_16x16x64_i8 v[84:87], v[116:119], v[190:193], v[84:87]
	v_mfma_i32_16x16x64_i8 v[80:83], v[128:131], v[186:189], v[80:83]
	v_mfma_i32_16x16x64_i8 v[80:83], v[142:145], v[190:193], v[80:83]
	v_mfma_i32_16x16x64_i8 v[88:91], v[128:131], v[172:175], v[88:91]
	v_mfma_i32_16x16x64_i8 v[88:91], v[142:145], v[182:185], v[88:91]
	v_mfma_i32_16x16x64_i8 v[28:31], v[146:149], v[172:175], v[28:31]
	v_mfma_i32_16x16x64_i8 v[28:31], v[150:153], v[182:185], v[28:31]
	v_mfma_i32_16x16x64_i8 v[24:27], v[154:157], v[172:175], v[24:27]
	v_mfma_i32_16x16x64_i8 v[24:27], v[168:171], v[182:185], v[24:27]
	v_mfma_i32_16x16x64_i8 v[16:19], v[154:157], v[186:189], v[16:19]
	v_mfma_i32_16x16x64_i8 v[16:19], v[168:171], v[190:193], v[16:19]
	v_mfma_i32_16x16x64_i8 v[20:23], v[146:149], v[186:189], v[20:23]
	v_mfma_i32_16x16x64_i8 v[20:23], v[150:153], v[190:193], v[20:23]
	s_setprio 0
	s_setprio 1
	v_mfma_i32_16x16x64_i8 v[12:15], v[146:149], v[194:197], v[12:15]
	v_mfma_i32_16x16x64_i8 v[12:15], v[150:153], v[198:201], v[12:15]
	v_mfma_i32_16x16x64_i8 v[8:11], v[154:157], v[194:197], v[8:11]
	v_mfma_i32_16x16x64_i8 v[8:11], v[168:171], v[198:201], v[8:11]
	v_mfma_i32_16x16x64_i8 v[0:3], v[154:157], v[206:209], v[0:3]
	v_mfma_i32_16x16x64_i8 v[0:3], v[168:171], v[210:213], v[0:3]
	v_mfma_i32_16x16x64_i8 v[4:7], v[146:149], v[206:209], v[4:7]
	v_mfma_i32_16x16x64_i8 v[4:7], v[150:153], v[210:213], v[4:7]
	v_mfma_i32_16x16x64_i8 v[64:67], v[128:131], v[206:209], v[64:67]
	v_mfma_i32_16x16x64_i8 v[64:67], v[142:145], v[210:213], v[64:67]
	v_mfma_i32_16x16x64_i8 v[72:75], v[128:131], v[194:197], v[72:75]
	v_mfma_i32_16x16x64_i8 v[72:75], v[142:145], v[198:201], v[72:75]
	s_setprio 2
	s_barrier
	v_mfma_i32_16x16x64_i8 v[76:79], v[112:115], v[194:197], v[76:79]
	v_mfma_i32_16x16x64_i8 v[76:79], v[116:119], v[198:201], v[76:79]
	v_mfma_i32_16x16x64_i8 v[68:71], v[112:115], v[206:209], v[68:71]
	v_mfma_i32_16x16x64_i8 v[68:71], v[116:119], v[210:213], v[68:71]
	s_setprio 0
	s_add_i32 s49, 0, 0x18000
	v_add_u32_e32 v136, s49, v179
	s_add_i32 s70, 0, 0x1c000
	ds_read_b128 v[112:115], v136
	ds_read_b128 v[116:119], v136 offset:1024
	ds_read_b128 v[128:131], v136 offset:2048
	ds_read_b128 v[142:145], v136 offset:3072
	v_add_u32_e32 v136, s70, v179
	ds_read_b128 v[146:149], v136
	ds_read_b128 v[150:153], v136 offset:1024
	ds_read_b128 v[154:157], v136 offset:2048
	ds_read_b128 v[168:171], v136 offset:3072
	s_mov_b32 m0, s51
	ds_read_b128 v[172:175], v203 offset:32768
	ds_read_b128 v[182:185], v203 offset:33792
	ds_read_b128 v[186:189], v203 offset:34816
	ds_read_b128 v[190:193], v203 offset:35840
	ds_read_b128 v[194:197], v203 offset:36864
	ds_read_b128 v[198:201], v203 offset:37888
	ds_read_b128 v[206:209], v203 offset:38912
	ds_read_b128 v[210:213], v203 offset:39936
	s_add_u32 s98, s100, s6
	s_addc_u32 s99, s101, s7
	global_load_lds_dwordx4 v158, s[98:99]
	s_mov_b32 m0, s52
	s_nop 0
	s_add_u32 s98, s100, s8
	s_addc_u32 s99, s101, s9
	global_load_lds_dwordx4 v158, s[98:99]
	s_waitcnt vmcnt(8)
	s_waitcnt lgkmcnt(0)
	s_barrier
	s_setprio 1
	s_waitcnt lgkmcnt(0)
	v_mfma_i32_16x16x64_i8 v[136:139], v[112:115], v[172:175], v[138:141]
	v_mfma_i32_16x16x64_i8 v[132:135], v[128:131], v[172:175], v[132:135]
	v_mfma_i32_16x16x64_i8 v[124:127], v[112:115], v[186:189], v[124:127]
	v_mfma_i32_16x16x64_i8 v[120:123], v[128:131], v[186:189], v[120:123]
	v_mfma_i32_16x16x64_i8 v[108:111], v[112:115], v[194:197], v[108:111]
	v_mfma_i32_16x16x64_i8 v[104:107], v[128:131], v[194:197], v[104:107]
	v_mfma_i32_16x16x64_i8 v[100:103], v[112:115], v[206:209], v[100:103]
	v_mfma_i32_16x16x64_i8 v[96:99], v[128:131], v[206:209], v[96:99]
	v_mfma_i32_16x16x64_i8 v[138:141], v[116:119], v[182:185], v[136:139]
	v_mfma_i32_16x16x64_i8 v[134:137], v[142:145], v[182:185], v[132:135]
	v_mfma_i32_16x16x64_i8 v[124:127], v[116:119], v[190:193], v[124:127]
	v_mfma_i32_16x16x64_i8 v[120:123], v[142:145], v[190:193], v[120:123]
	v_mfma_i32_16x16x64_i8 v[108:111], v[116:119], v[198:201], v[108:111]
	v_mfma_i32_16x16x64_i8 v[104:107], v[142:145], v[198:201], v[104:107]
	v_mfma_i32_16x16x64_i8 v[100:103], v[116:119], v[210:213], v[100:103]
	v_mfma_i32_16x16x64_i8 v[96:99], v[142:145], v[210:213], v[96:99]
	s_setprio 0
	s_setprio 1
	v_mfma_i32_16x16x64_i8 v[60:63], v[146:149], v[172:175], v[60:63]
	v_mfma_i32_16x16x64_i8 v[60:63], v[150:153], v[182:185], v[60:63]
	v_mfma_i32_16x16x64_i8 v[56:59], v[154:157], v[172:175], v[56:59]
	v_mfma_i32_16x16x64_i8 v[56:59], v[168:171], v[182:185], v[56:59]
	v_mfma_i32_16x16x64_i8 v[52:55], v[146:149], v[186:189], v[52:55]
	v_mfma_i32_16x16x64_i8 v[52:55], v[150:153], v[190:193], v[52:55]
	v_mfma_i32_16x16x64_i8 v[48:51], v[154:157], v[186:189], v[48:51]
	v_mfma_i32_16x16x64_i8 v[48:51], v[168:171], v[190:193], v[48:51]
	v_mfma_i32_16x16x64_i8 v[44:47], v[146:149], v[194:197], v[44:47]
	v_mfma_i32_16x16x64_i8 v[44:47], v[150:153], v[198:201], v[44:47]
	v_mfma_i32_16x16x64_i8 v[40:43], v[154:157], v[194:197], v[40:43]
	v_mfma_i32_16x16x64_i8 v[40:43], v[168:171], v[198:201], v[40:43]
	s_setprio 2
	s_barrier
	v_mfma_i32_16x16x64_i8 v[36:39], v[146:149], v[206:209], v[36:39]
	v_mfma_i32_16x16x64_i8 v[36:39], v[150:153], v[210:213], v[36:39]
	v_mfma_i32_16x16x64_i8 v[32:35], v[154:157], v[206:209], v[32:35]
	v_mfma_i32_16x16x64_i8 v[32:35], v[168:171], v[210:213], v[32:35]
	s_setprio 0
	s_add_i32 s49, s49, s33
	s_mov_b32 m0, s49
	ds_read_b128 v[172:175], v203 offset:49152
	ds_read_b128 v[182:185], v203 offset:50176
	ds_read_b128 v[186:189], v203 offset:51200
	ds_read_b128 v[190:193], v203 offset:52224
	ds_read_b128 v[194:197], v203 offset:53248
	ds_read_b128 v[198:201], v203 offset:54272
	ds_read_b128 v[206:209], v203 offset:55296
	ds_read_b128 v[210:213], v203 offset:56320
	s_add_u32 s98, s72, s16
	s_addc_u32 s99, s73, s17
	global_load_lds_dwordx4 v160, s[98:99]
	s_add_i32 m0, s49, 0x2000
	s_add_i32 s49, s70, s33
	s_add_u32 s98, s72, s18
	s_addc_u32 s99, s73, s19
	global_load_lds_dwordx4 v160, s[98:99]
	s_mov_b32 m0, s49
	s_nop 0
	s_add_u32 s98, s72, s20
	s_addc_u32 s99, s73, s21
	global_load_lds_dwordx4 v160, s[98:99]
	s_add_i32 m0, s49, 0x2000
	s_nop 0
	s_add_u32 s98, s72, s30
	s_addc_u32 s99, s73, s31
	global_load_lds_dwordx4 v160, s[98:99]
	s_mov_b32 m0, s54
	s_nop 0
	s_add_u32 s98, s100, s16
	s_addc_u32 s99, s101, s17
	global_load_lds_dwordx4 v158, s[98:99]
	s_mov_b32 m0, s55
	s_nop 0
	s_add_u32 s98, s100, s18
	s_addc_u32 s99, s101, s19
	global_load_lds_dwordx4 v158, s[98:99]
	s_waitcnt vmcnt(8)
	s_waitcnt lgkmcnt(0)
	s_barrier
	s_setprio 1
	s_waitcnt lgkmcnt(0)
	v_mfma_i32_16x16x64_i8 v[92:95], v[112:115], v[172:175], v[92:95]
	v_mfma_i32_16x16x64_i8 v[92:95], v[116:119], v[182:185], v[92:95]
	v_mfma_i32_16x16x64_i8 v[84:87], v[112:115], v[186:189], v[84:87]
	v_mfma_i32_16x16x64_i8 v[84:87], v[116:119], v[190:193], v[84:87]
	v_mfma_i32_16x16x64_i8 v[80:83], v[128:131], v[186:189], v[80:83]
	v_mfma_i32_16x16x64_i8 v[80:83], v[142:145], v[190:193], v[80:83]
	v_mfma_i32_16x16x64_i8 v[88:91], v[128:131], v[172:175], v[88:91]
	v_mfma_i32_16x16x64_i8 v[88:91], v[142:145], v[182:185], v[88:91]
	v_mfma_i32_16x16x64_i8 v[28:31], v[146:149], v[172:175], v[28:31]
	v_mfma_i32_16x16x64_i8 v[28:31], v[150:153], v[182:185], v[28:31]
	v_mfma_i32_16x16x64_i8 v[24:27], v[154:157], v[172:175], v[24:27]
	v_mfma_i32_16x16x64_i8 v[24:27], v[168:171], v[182:185], v[24:27]
	v_mfma_i32_16x16x64_i8 v[16:19], v[154:157], v[186:189], v[16:19]
	v_mfma_i32_16x16x64_i8 v[16:19], v[168:171], v[190:193], v[16:19]
	v_mfma_i32_16x16x64_i8 v[20:23], v[146:149], v[186:189], v[20:23]
	v_mfma_i32_16x16x64_i8 v[20:23], v[150:153], v[190:193], v[20:23]
	s_setprio 0
	s_setprio 1
	v_mfma_i32_16x16x64_i8 v[12:15], v[146:149], v[194:197], v[12:15]
	v_mfma_i32_16x16x64_i8 v[12:15], v[150:153], v[198:201], v[12:15]
	v_mfma_i32_16x16x64_i8 v[8:11], v[154:157], v[194:197], v[8:11]
	v_mfma_i32_16x16x64_i8 v[8:11], v[168:171], v[198:201], v[8:11]
	v_mfma_i32_16x16x64_i8 v[0:3], v[154:157], v[206:209], v[0:3]
	v_mfma_i32_16x16x64_i8 v[0:3], v[168:171], v[210:213], v[0:3]
	v_mfma_i32_16x16x64_i8 v[4:7], v[146:149], v[206:209], v[4:7]
	v_mfma_i32_16x16x64_i8 v[4:7], v[150:153], v[210:213], v[4:7]
	v_mfma_i32_16x16x64_i8 v[64:67], v[128:131], v[206:209], v[64:67]
	v_mfma_i32_16x16x64_i8 v[64:67], v[142:145], v[210:213], v[64:67]
	v_mfma_i32_16x16x64_i8 v[72:75], v[128:131], v[194:197], v[72:75]
	v_mfma_i32_16x16x64_i8 v[72:75], v[142:145], v[198:201], v[72:75]
	s_setprio 2
	s_barrier
	v_mfma_i32_16x16x64_i8 v[76:79], v[112:115], v[194:197], v[76:79]
	v_mfma_i32_16x16x64_i8 v[76:79], v[116:119], v[198:201], v[76:79]
	v_mfma_i32_16x16x64_i8 v[68:71], v[112:115], v[206:209], v[68:71]
	v_mfma_i32_16x16x64_i8 v[68:71], v[116:119], v[210:213], v[68:71]
	s_setprio 0
	s_add_i32 s48, s48, 2
	s_add_u32 s68, s68, 0x100
	s_addc_u32 s69, s69, 0
	s_add_u32 s46, s46, 0x100
	s_addc_u32 s47, s47, 0
	s_cmp_gt_u32 s48, 29
	s_cbranch_scc0 .LBB0_1180
	s_and_b64 vcc, exec, s[34:35]
	s_cbranch_vccz .LBB0_1183
	s_barrier
